# all eight GEMM main loops: hipcc's per-segment s_setprio flips deleted
# baseline (speedup 1.0000x reference)
; #define PG8_STAGE(bufoff, gbase, voff) do { _Pragma("unroll") for (int _i = 0; _i < 2; ++_i) \
;         __builtin_amdgcn_global_load_lds((const unsigned*)((const char*)(gbase) + (voff)[_i]), (LAS unsigned*)(lds + (bufoff) + ldsw + _i * 8192), 16, 0, 0); } while (0)
; #define PG8_LDA(dst, b, h) do { _Pragma("unroll") for (int m = 0; m < 4; ++m) _Pragma("unroll") for (int k = 0; k < 2; ++k) dst[m][k] = *(const LAS bf16x8*)(lds + PG8_SA(b, h) + aoff + m * 2048 + k * 1024); } while (0)
; #define PG8_LDB(dst, b, h) do { _Pragma("unroll") for (int n = 0; n < 2; ++n) _Pragma("unroll") for (int k = 0; k < 2; ++k) dst[n][k] = *(const LAS bf16x8*)(lds + PG8_SB(b, h) + boff + n * 2048 + k * 1024); } while (0)
; #define PG8_MMA(ai, bj, At, Bt) do { __builtin_amdgcn_s_setprio(1); _Pragma("unroll") for (int m = 0; m < 4; ++m) _Pragma("unroll") for (int n = 0; n < 2; ++n) _Pragma("unroll") for (int k = 0; k < 2; ++k) \
;         acc[ai][bj][m][n] = __builtin_amdgcn_mfma_f32_16x16x32_bf16(Bt[n][k], At[m][k], acc[ai][bj][m][n], 0, 0, 0); __builtin_amdgcn_s_setprio(0); } while (0)
; #define PG8_WAIT_L(n) asm volatile("s_waitcnt lgkmcnt(" #n ")" ::: "memory")
; #define PG8_BAR __builtin_amdgcn_s_barrier()
; #define PG8_SCHED __builtin_amdgcn_sched_barrier(0)
; template <class Epi>
; __device__ __forceinline__ void gemm_phase(LAS unsigned char* lds, const Gemm g, const StaticOrder& S, const Epi& E) {
;     ...
;             PG8_LDB(B0, 0, 0); PG8_SCHED; PG8_LDA(At, 0, 0); PG8_STAGE(PG8_SA(1, 1), a1 + hstep, voffA);
;             PG8_WAIT_L(8); PG8_BAR; PG8_WAIT_L(0); PG8_MMA(0, 0, At, B0); PG8_BAR; PG8_SCHED;
;             PG8_LDB(B1, 0, 1); PG8_STAGE(PG8_SB(0, 0), b2, voffB);
;             PG8_BAR; PG8_WAIT_L(0); PG8_MMA(0, 1, At, B1); PG8_BAR;
;             PG8_LDA(At, 0, 1); PG8_STAGE(PG8_SA(0, 0), a2, voffA);
;             PG8_BAR; PG8_WAIT_L(0); PG8_MMA(1, 0, At, B0); PG8_BAR; PG8_SCHED;
.LBB0_400:
	s_add_i32 s46, s28, 2
	s_add_u32 s29, s26, 0xe4e00080
	s_addc_u32 s30, s27, -1
	s_cmp_lg_u32 s45, s28
	s_cselect_b32 s31, s30, 0
	s_cselect_b32 s30, s29, 0
	s_add_u32 s28, s4, s30
	s_addc_u32 s29, s5, s31
	s_add_i32 s47, 0, 0x10000
	v_add_u32_e32 v154, s47, v140
	ds_read_b128 v[142:145], v154
	ds_read_b128 v[146:149], v154 offset:1024
	ds_read_b128 v[150:153], v154 offset:2048
	ds_read_b128 v[154:157], v154 offset:3072
	s_add_u32 s30, s6, s30
	s_addc_u32 s31, s7, s31
	v_lshl_add_u64 v[190:191], v[136:137], 0, s[26:27]
	s_add_i32 m0, s38, 0xc000
	ds_read_b128 v[158:161], v141
	ds_read_b128 v[162:165], v141 offset:1024
	ds_read_b128 v[166:169], v141 offset:2048
	ds_read_b128 v[170:173], v141 offset:3072
	ds_read_b128 v[174:177], v141 offset:4096
	ds_read_b128 v[178:181], v141 offset:5120
	ds_read_b128 v[182:185], v141 offset:6144
	ds_read_b128 v[186:189], v141 offset:7168
	global_load_lds_dwordx4 v[190:191], off
	v_lshl_add_u64 v[190:191], v[134:135], 0, s[26:27]
	s_add_i32 m0, s38, 0xe000
	s_nop 0
	global_load_lds_dwordx4 v[190:191], off
	s_waitcnt lgkmcnt(8)
	s_barrier
	s_waitcnt lgkmcnt(0)
	s_waitcnt lgkmcnt(0)
	v_mfma_f32_16x16x32_bf16 v[124:127], v[142:145], v[158:161], v[124:127]
	v_mfma_f32_16x16x32_bf16 v[120:123], v[150:153], v[158:161], v[120:123]
	v_mfma_f32_16x16x32_bf16 v[108:111], v[142:145], v[166:169], v[108:111]
	v_mfma_f32_16x16x32_bf16 v[104:107], v[150:153], v[166:169], v[104:107]
	v_mfma_f32_16x16x32_bf16 v[92:95], v[142:145], v[174:177], v[92:95]
	v_mfma_f32_16x16x32_bf16 v[88:91], v[150:153], v[174:177], v[88:91]
	v_mfma_f32_16x16x32_bf16 v[76:79], v[142:145], v[182:185], v[76:79]
	v_mfma_f32_16x16x32_bf16 v[72:75], v[150:153], v[182:185], v[72:75]
	v_mfma_f32_16x16x32_bf16 v[124:127], v[146:149], v[162:165], v[124:127]
	v_mfma_f32_16x16x32_bf16 v[120:123], v[154:157], v[162:165], v[120:123]
	v_mfma_f32_16x16x32_bf16 v[108:111], v[146:149], v[170:173], v[108:111]
	v_mfma_f32_16x16x32_bf16 v[104:107], v[154:157], v[170:173], v[104:107]
	v_mfma_f32_16x16x32_bf16 v[92:95], v[146:149], v[178:181], v[92:95]
	v_mfma_f32_16x16x32_bf16 v[88:91], v[154:157], v[178:181], v[88:91]
	v_mfma_f32_16x16x32_bf16 v[76:79], v[146:149], v[186:189], v[76:79]
	v_mfma_f32_16x16x32_bf16 v[72:75], v[154:157], v[186:189], v[72:75]
	s_barrier
	s_add_i32 s48, 0, 0x14000
	v_add_u32_e32 v190, s48, v140
	s_add_i32 s47, s47, s37
	ds_read_b128 v[202:205], v190
	ds_read_b128 v[206:209], v190 offset:1024
	ds_read_b128 v[210:213], v190 offset:2048
	ds_read_b128 v[214:217], v190 offset:3072
	v_lshl_add_u64 v[190:191], s[30:31], 0, v[194:195]
	s_mov_b32 m0, s47
	v_lshl_add_u64 v[218:219], s[30:31], 0, v[132:133]
	global_load_lds_dwordx4 v[190:191], off
	s_add_i32 m0, s47, 0x2000
	s_nop 0
	global_load_lds_dwordx4 v[218:219], off
	s_barrier
	s_waitcnt lgkmcnt(0)
	s_waitcnt lgkmcnt(0)
	v_mfma_f32_16x16x32_bf16 v[116:119], v[202:205], v[158:161], v[116:119]
	v_mfma_f32_16x16x32_bf16 v[112:115], v[210:213], v[158:161], v[112:115]
	v_mfma_f32_16x16x32_bf16 v[100:103], v[202:205], v[166:169], v[100:103]
	v_mfma_f32_16x16x32_bf16 v[96:99], v[210:213], v[166:169], v[96:99]
	v_mfma_f32_16x16x32_bf16 v[84:87], v[202:205], v[174:177], v[84:87]
	v_mfma_f32_16x16x32_bf16 v[80:83], v[210:213], v[174:177], v[80:83]
	v_mfma_f32_16x16x32_bf16 v[68:71], v[202:205], v[182:185], v[68:71]
	v_mfma_f32_16x16x32_bf16 v[64:67], v[210:213], v[182:185], v[64:67]
	v_mfma_f32_16x16x32_bf16 v[116:119], v[206:209], v[162:165], v[116:119]
	v_mfma_f32_16x16x32_bf16 v[112:115], v[214:217], v[162:165], v[112:115]
	v_mfma_f32_16x16x32_bf16 v[100:103], v[206:209], v[170:173], v[100:103]
	v_mfma_f32_16x16x32_bf16 v[96:99], v[214:217], v[170:173], v[96:99]
	v_mfma_f32_16x16x32_bf16 v[84:87], v[206:209], v[178:181], v[84:87]
	v_mfma_f32_16x16x32_bf16 v[80:83], v[214:217], v[178:181], v[80:83]
	v_mfma_f32_16x16x32_bf16 v[68:71], v[206:209], v[186:189], v[68:71]
	v_mfma_f32_16x16x32_bf16 v[64:67], v[214:217], v[186:189], v[64:67]
	s_mov_b32 m0, s38
	v_lshl_add_u64 v[220:221], s[28:29], 0, v[128:129]
	s_barrier
	ds_read_b128 v[158:161], v141 offset:16384
	ds_read_b128 v[162:165], v141 offset:17408
	ds_read_b128 v[166:169], v141 offset:18432
	ds_read_b128 v[170:173], v141 offset:19456
	ds_read_b128 v[174:177], v141 offset:20480
	ds_read_b128 v[178:181], v141 offset:21504
	ds_read_b128 v[182:185], v141 offset:22528
	ds_read_b128 v[186:189], v141 offset:23552
	global_load_lds_dwordx4 v[220:221], off
	v_lshl_add_u64 v[222:223], s[28:29], 0, v[130:131]
	s_mov_b32 m0, s39
	s_nop 0
	global_load_lds_dwordx4 v[222:223], off
	s_barrier
	s_waitcnt lgkmcnt(0)
	s_waitcnt lgkmcnt(0)
	v_mfma_f32_16x16x32_bf16 v[60:63], v[142:145], v[158:161], v[60:63]
	v_mfma_f32_16x16x32_bf16 v[56:59], v[150:153], v[158:161], v[56:59]
	v_mfma_f32_16x16x32_bf16 v[44:47], v[142:145], v[166:169], v[44:47]
	v_mfma_f32_16x16x32_bf16 v[40:43], v[150:153], v[166:169], v[40:43]
	v_mfma_f32_16x16x32_bf16 v[28:31], v[142:145], v[174:177], v[28:31]
	v_mfma_f32_16x16x32_bf16 v[24:27], v[150:153], v[174:177], v[24:27]
	v_mfma_f32_16x16x32_bf16 v[12:15], v[142:145], v[182:185], v[12:15]
	v_mfma_f32_16x16x32_bf16 v[8:11], v[150:153], v[182:185], v[8:11]
	v_mfma_f32_16x16x32_bf16 v[60:63], v[146:149], v[162:165], v[60:63]
	v_mfma_f32_16x16x32_bf16 v[56:59], v[154:157], v[162:165], v[56:59]
	v_mfma_f32_16x16x32_bf16 v[44:47], v[146:149], v[170:173], v[44:47]
	v_mfma_f32_16x16x32_bf16 v[40:43], v[154:157], v[170:173], v[40:43]
	v_mfma_f32_16x16x32_bf16 v[28:31], v[146:149], v[178:181], v[28:31]
	v_mfma_f32_16x16x32_bf16 v[24:27], v[154:157], v[178:181], v[24:27]
	v_mfma_f32_16x16x32_bf16 v[12:15], v[146:149], v[186:189], v[12:15]
	v_mfma_f32_16x16x32_bf16 v[8:11], v[154:157], v[186:189], v[8:11]
	s_barrier
; #define PG8_STAGE(bufoff, gbase, voff) do { _Pragma("unroll") for (int _i = 0; _i < 2; ++_i) \
;         __builtin_amdgcn_global_load_lds((const unsigned*)((const char*)(gbase) + (voff)[_i]), (LAS unsigned*)(lds + (bufoff) + ldsw + _i * 8192), 16, 0, 0); } while (0)
; #define PG8_LDA(dst, b, h) do { _Pragma("unroll") for (int m = 0; m < 4; ++m) _Pragma("unroll") for (int k = 0; k < 2; ++k) dst[m][k] = *(const LAS bf16x8*)(lds + PG8_SA(b, h) + aoff + m * 2048 + k * 1024); } while (0)
; #define PG8_LDB(dst, b, h) do { _Pragma("unroll") for (int n = 0; n < 2; ++n) _Pragma("unroll") for (int k = 0; k < 2; ++k) dst[n][k] = *(const LAS bf16x8*)(lds + PG8_SB(b, h) + boff + n * 2048 + k * 1024); } while (0)
; #define PG8_MMA(ai, bj, At, Bt) do { __builtin_amdgcn_s_setprio(1); _Pragma("unroll") for (int m = 0; m < 4; ++m) _Pragma("unroll") for (int n = 0; n < 2; ++n) _Pragma("unroll") for (int k = 0; k < 2; ++k) \
;         acc[ai][bj][m][n] = __builtin_amdgcn_mfma_f32_16x16x32_bf16(Bt[n][k], At[m][k], acc[ai][bj][m][n], 0, 0, 0); __builtin_amdgcn_s_setprio(0); } while (0)
; #define PG8_WAIT_V(n) asm volatile("s_waitcnt vmcnt(" #n ")" ::: "memory")
; #define PG8_WAIT_L(n) asm volatile("s_waitcnt lgkmcnt(" #n ")" ::: "memory")
; #define PG8_BAR __builtin_amdgcn_s_barrier()
; #define PG8_SCHED __builtin_amdgcn_sched_barrier(0)
; template <class Epi>
; __device__ __forceinline__ void gemm_phase(LAS unsigned char* lds, const Gemm g, const StaticOrder& S, const Epi& E) {
;     ...
;             PG8_STAGE(PG8_SB(0, 1), b2 + hstep, voffB);
;             PG8_WAIT_V(6); PG8_BAR; PG8_MMA(1, 1, At, B1); PG8_BAR;
;             PG8_LDB(B0, 1, 0); PG8_SCHED; PG8_LDA(At, 1, 0); PG8_STAGE(PG8_SA(0, 1), a2 + hstep, voffA);
;             PG8_WAIT_L(8); PG8_BAR; PG8_WAIT_L(0); PG8_MMA(0, 0, At, B0); PG8_BAR; PG8_SCHED;
;             PG8_LDB(B1, 1, 1); PG8_STAGE(PG8_SB(1, 0), b3, voffB);
	s_add_u32 s30, s30, s24
	s_addc_u32 s31, s31, s25
	s_add_i32 s47, s48, s37
	v_lshl_add_u64 v[224:225], s[30:31], 0, v[194:195]
	s_mov_b32 m0, s47
	v_lshl_add_u64 v[226:227], s[30:31], 0, v[132:133]
	global_load_lds_dwordx4 v[224:225], off
	s_add_i32 m0, s47, 0x2000
	s_nop 0
	global_load_lds_dwordx4 v[226:227], off
	s_waitcnt vmcnt(6)
	s_barrier
	v_mfma_f32_16x16x32_bf16 v[52:55], v[202:205], v[158:161], v[52:55]
	v_mfma_f32_16x16x32_bf16 v[48:51], v[210:213], v[158:161], v[48:51]
	v_mfma_f32_16x16x32_bf16 v[36:39], v[202:205], v[166:169], v[36:39]
	v_mfma_f32_16x16x32_bf16 v[32:35], v[210:213], v[166:169], v[32:35]
	v_mfma_f32_16x16x32_bf16 v[20:23], v[202:205], v[174:177], v[20:23]
	v_mfma_f32_16x16x32_bf16 v[16:19], v[210:213], v[174:177], v[16:19]
	v_mfma_f32_16x16x32_bf16 v[4:7], v[202:205], v[182:185], v[4:7]
	v_mfma_f32_16x16x32_bf16 v[0:3], v[210:213], v[182:185], v[0:3]
	v_mfma_f32_16x16x32_bf16 v[52:55], v[206:209], v[162:165], v[52:55]
	v_mfma_f32_16x16x32_bf16 v[48:51], v[214:217], v[162:165], v[48:51]
	v_mfma_f32_16x16x32_bf16 v[36:39], v[206:209], v[170:173], v[36:39]
	v_mfma_f32_16x16x32_bf16 v[32:35], v[214:217], v[170:173], v[32:35]
	v_mfma_f32_16x16x32_bf16 v[20:23], v[206:209], v[178:181], v[20:23]
	v_mfma_f32_16x16x32_bf16 v[16:19], v[214:217], v[178:181], v[16:19]
	v_mfma_f32_16x16x32_bf16 v[4:7], v[206:209], v[186:189], v[4:7]
	v_mfma_f32_16x16x32_bf16 v[0:3], v[214:217], v[186:189], v[0:3]
	s_add_i32 s30, 0, 0x18000
	v_add_u32_e32 v154, s30, v140
	s_barrier
	ds_read_b128 v[142:145], v154
	ds_read_b128 v[146:149], v154 offset:1024
	ds_read_b128 v[150:153], v154 offset:2048
	ds_read_b128 v[154:157], v154 offset:3072
	s_add_u32 s28, s28, s24
	s_addc_u32 s29, s29, s25
	s_mov_b32 m0, s40
	v_lshl_add_u64 v[202:203], s[28:29], 0, v[128:129]
	ds_read_b128 v[158:161], v141 offset:32768
	ds_read_b128 v[162:165], v141 offset:33792
	ds_read_b128 v[166:169], v141 offset:34816
	ds_read_b128 v[170:173], v141 offset:35840
	ds_read_b128 v[174:177], v141 offset:36864
	ds_read_b128 v[178:181], v141 offset:37888
	ds_read_b128 v[182:185], v141 offset:38912
	ds_read_b128 v[186:189], v141 offset:39936
	global_load_lds_dwordx4 v[202:203], off
	v_lshl_add_u64 v[202:203], s[28:29], 0, v[130:131]
	s_mov_b32 m0, s41
	s_nop 0
	global_load_lds_dwordx4 v[202:203], off
	s_waitcnt lgkmcnt(8)
	s_barrier
	s_waitcnt lgkmcnt(0)
	s_waitcnt lgkmcnt(0)
	v_mfma_f32_16x16x32_bf16 v[124:127], v[142:145], v[158:161], v[124:127]
	v_mfma_f32_16x16x32_bf16 v[120:123], v[150:153], v[158:161], v[120:123]
	v_mfma_f32_16x16x32_bf16 v[108:111], v[142:145], v[166:169], v[108:111]
	v_mfma_f32_16x16x32_bf16 v[104:107], v[150:153], v[166:169], v[104:107]
	v_mfma_f32_16x16x32_bf16 v[92:95], v[142:145], v[174:177], v[92:95]
	v_mfma_f32_16x16x32_bf16 v[88:91], v[150:153], v[174:177], v[88:91]
	v_mfma_f32_16x16x32_bf16 v[76:79], v[142:145], v[182:185], v[76:79]
	v_mfma_f32_16x16x32_bf16 v[72:75], v[150:153], v[182:185], v[72:75]
	v_mfma_f32_16x16x32_bf16 v[124:127], v[146:149], v[162:165], v[124:127]
	v_mfma_f32_16x16x32_bf16 v[120:123], v[154:157], v[162:165], v[120:123]
	v_mfma_f32_16x16x32_bf16 v[108:111], v[146:149], v[170:173], v[108:111]
	v_mfma_f32_16x16x32_bf16 v[104:107], v[154:157], v[170:173], v[104:107]
	v_mfma_f32_16x16x32_bf16 v[92:95], v[146:149], v[178:181], v[92:95]
	v_mfma_f32_16x16x32_bf16 v[88:91], v[154:157], v[178:181], v[88:91]
	v_mfma_f32_16x16x32_bf16 v[76:79], v[146:149], v[186:189], v[76:79]
	v_mfma_f32_16x16x32_bf16 v[72:75], v[154:157], v[186:189], v[72:75]
	s_barrier
	s_add_i32 s28, 0, 0x1c000
	s_add_i32 s29, s30, s37
	v_add_u32_e32 v193, s28, v140
	v_lshl_add_u64 v[190:191], v[190:191], 0, s[50:51]
	s_mov_b32 m0, s29
	ds_read_b128 v[202:205], v193
	ds_read_b128 v[206:209], v193 offset:1024
	ds_read_b128 v[210:213], v193 offset:2048
	ds_read_b128 v[214:217], v193 offset:3072
	global_load_lds_dwordx4 v[190:191], off
	v_lshl_add_u64 v[190:191], v[218:219], 0, s[50:51]
	s_add_i32 m0, s29, 0x2000
	s_nop 0
	global_load_lds_dwordx4 v[190:191], off
	s_barrier
; #define PG8_STAGE(bufoff, gbase, voff) do { _Pragma("unroll") for (int _i = 0; _i < 2; ++_i) \
;         __builtin_amdgcn_global_load_lds((const unsigned*)((const char*)(gbase) + (voff)[_i]), (LAS unsigned*)(lds + (bufoff) + ldsw + _i * 8192), 16, 0, 0); } while (0)
; #define PG8_LDA(dst, b, h) do { _Pragma("unroll") for (int m = 0; m < 4; ++m) _Pragma("unroll") for (int k = 0; k < 2; ++k) dst[m][k] = *(const LAS bf16x8*)(lds + PG8_SA(b, h) + aoff + m * 2048 + k * 1024); } while (0)
; #define PG8_LDB(dst, b, h) do { _Pragma("unroll") for (int n = 0; n < 2; ++n) _Pragma("unroll") for (int k = 0; k < 2; ++k) dst[n][k] = *(const LAS bf16x8*)(lds + PG8_SB(b, h) + boff + n * 2048 + k * 1024); } while (0)
; #define PG8_MMA(ai, bj, At, Bt) do { __builtin_amdgcn_s_setprio(1); _Pragma("unroll") for (int m = 0; m < 4; ++m) _Pragma("unroll") for (int n = 0; n < 2; ++n) _Pragma("unroll") for (int k = 0; k < 2; ++k) \
;         acc[ai][bj][m][n] = __builtin_amdgcn_mfma_f32_16x16x32_bf16(Bt[n][k], At[m][k], acc[ai][bj][m][n], 0, 0, 0); __builtin_amdgcn_s_setprio(0); } while (0)
; #define PG8_WAIT_V(n) asm volatile("s_waitcnt vmcnt(" #n ")" ::: "memory")
; #define PG8_WAIT_L(n) asm volatile("s_waitcnt lgkmcnt(" #n ")" ::: "memory")
; #define PG8_BAR __builtin_amdgcn_s_barrier()
; #define PG8_SCHED __builtin_amdgcn_sched_barrier(0)
; template <class Epi>
; __device__ __forceinline__ void gemm_phase(LAS unsigned char* lds, const Gemm g, const StaticOrder& S, const Epi& E) {
;     ...
;             PG8_LDB(B1, 1, 1); PG8_STAGE(PG8_SB(1, 0), b3, voffB);
;             PG8_BAR; PG8_WAIT_L(0); PG8_MMA(0, 1, At, B1); PG8_BAR;
;             PG8_LDA(At, 1, 1); PG8_STAGE(PG8_SA(1, 0), a3, voffA);
;             PG8_BAR; PG8_WAIT_L(0); PG8_MMA(1, 0, At, B0); PG8_BAR; PG8_SCHED;
;             PG8_STAGE(PG8_SB(1, 1), b3 + hstep, voffB);
;             PG8_WAIT_V(6); PG8_BAR; PG8_MMA(1, 1, At, B1); PG8_BAR;
;         }
	s_waitcnt lgkmcnt(0)
	s_waitcnt lgkmcnt(0)
	v_mfma_f32_16x16x32_bf16 v[116:119], v[202:205], v[158:161], v[116:119]
	v_mfma_f32_16x16x32_bf16 v[112:115], v[210:213], v[158:161], v[112:115]
	v_mfma_f32_16x16x32_bf16 v[100:103], v[202:205], v[166:169], v[100:103]
	v_mfma_f32_16x16x32_bf16 v[96:99], v[210:213], v[166:169], v[96:99]
	v_mfma_f32_16x16x32_bf16 v[84:87], v[202:205], v[174:177], v[84:87]
	v_mfma_f32_16x16x32_bf16 v[80:83], v[210:213], v[174:177], v[80:83]
	v_mfma_f32_16x16x32_bf16 v[68:71], v[202:205], v[182:185], v[68:71]
	v_mfma_f32_16x16x32_bf16 v[64:67], v[210:213], v[182:185], v[64:67]
	v_mfma_f32_16x16x32_bf16 v[116:119], v[206:209], v[162:165], v[116:119]
	v_mfma_f32_16x16x32_bf16 v[112:115], v[214:217], v[162:165], v[112:115]
	v_mfma_f32_16x16x32_bf16 v[100:103], v[206:209], v[170:173], v[100:103]
	v_mfma_f32_16x16x32_bf16 v[96:99], v[214:217], v[170:173], v[96:99]
	v_mfma_f32_16x16x32_bf16 v[84:87], v[206:209], v[178:181], v[84:87]
	v_mfma_f32_16x16x32_bf16 v[80:83], v[214:217], v[178:181], v[80:83]
	v_mfma_f32_16x16x32_bf16 v[68:71], v[206:209], v[186:189], v[68:71]
	v_mfma_f32_16x16x32_bf16 v[64:67], v[214:217], v[186:189], v[64:67]
	s_mov_b32 m0, s42
	v_lshl_add_u64 v[190:191], v[220:221], 0, s[50:51]
	s_barrier
	ds_read_b128 v[158:161], v141 offset:49152
	ds_read_b128 v[162:165], v141 offset:50176
	ds_read_b128 v[166:169], v141 offset:51200
	ds_read_b128 v[170:173], v141 offset:52224
	ds_read_b128 v[174:177], v141 offset:53248
	ds_read_b128 v[178:181], v141 offset:54272
	ds_read_b128 v[182:185], v141 offset:55296
	ds_read_b128 v[186:189], v141 offset:56320
	global_load_lds_dwordx4 v[190:191], off
	v_lshl_add_u64 v[190:191], v[222:223], 0, s[50:51]
	s_mov_b32 m0, s43
	s_nop 0
	global_load_lds_dwordx4 v[190:191], off
	s_barrier
	s_waitcnt lgkmcnt(0)
	s_waitcnt lgkmcnt(0)
	v_mfma_f32_16x16x32_bf16 v[60:63], v[142:145], v[158:161], v[60:63]
	v_mfma_f32_16x16x32_bf16 v[56:59], v[150:153], v[158:161], v[56:59]
	v_mfma_f32_16x16x32_bf16 v[44:47], v[142:145], v[166:169], v[44:47]
	v_mfma_f32_16x16x32_bf16 v[40:43], v[150:153], v[166:169], v[40:43]
	v_mfma_f32_16x16x32_bf16 v[28:31], v[142:145], v[174:177], v[28:31]
	v_mfma_f32_16x16x32_bf16 v[24:27], v[150:153], v[174:177], v[24:27]
	v_mfma_f32_16x16x32_bf16 v[12:15], v[142:145], v[182:185], v[12:15]
	v_mfma_f32_16x16x32_bf16 v[8:11], v[150:153], v[182:185], v[8:11]
	v_mfma_f32_16x16x32_bf16 v[60:63], v[146:149], v[162:165], v[60:63]
	v_mfma_f32_16x16x32_bf16 v[56:59], v[154:157], v[162:165], v[56:59]
	v_mfma_f32_16x16x32_bf16 v[44:47], v[146:149], v[170:173], v[44:47]
	v_mfma_f32_16x16x32_bf16 v[40:43], v[154:157], v[170:173], v[40:43]
	v_mfma_f32_16x16x32_bf16 v[28:31], v[146:149], v[178:181], v[28:31]
	v_mfma_f32_16x16x32_bf16 v[24:27], v[154:157], v[178:181], v[24:27]
	v_mfma_f32_16x16x32_bf16 v[12:15], v[146:149], v[186:189], v[12:15]
	v_mfma_f32_16x16x32_bf16 v[8:11], v[154:157], v[186:189], v[8:11]
	s_barrier
	s_add_i32 s28, s28, s37
	v_lshl_add_u64 v[142:143], v[224:225], 0, s[50:51]
	s_mov_b32 m0, s28
	s_nop 0
	global_load_lds_dwordx4 v[142:143], off
	v_lshl_add_u64 v[142:143], v[226:227], 0, s[50:51]
	s_add_i32 m0, s28, 0x2000
	s_nop 0
	global_load_lds_dwordx4 v[142:143], off
	s_waitcnt vmcnt(6)
	s_barrier
	v_mfma_f32_16x16x32_bf16 v[52:55], v[202:205], v[158:161], v[52:55]
	v_mfma_f32_16x16x32_bf16 v[48:51], v[210:213], v[158:161], v[48:51]
	v_mfma_f32_16x16x32_bf16 v[36:39], v[202:205], v[166:169], v[36:39]
	v_mfma_f32_16x16x32_bf16 v[32:35], v[210:213], v[166:169], v[32:35]
	v_mfma_f32_16x16x32_bf16 v[20:23], v[202:205], v[174:177], v[20:23]
	v_mfma_f32_16x16x32_bf16 v[16:19], v[210:213], v[174:177], v[16:19]
	v_mfma_f32_16x16x32_bf16 v[4:7], v[202:205], v[182:185], v[4:7]
	v_mfma_f32_16x16x32_bf16 v[0:3], v[210:213], v[182:185], v[0:3]
	v_mfma_f32_16x16x32_bf16 v[52:55], v[206:209], v[162:165], v[52:55]
	v_mfma_f32_16x16x32_bf16 v[48:51], v[214:217], v[162:165], v[48:51]
	v_mfma_f32_16x16x32_bf16 v[36:39], v[206:209], v[170:173], v[36:39]
	v_mfma_f32_16x16x32_bf16 v[32:35], v[214:217], v[170:173], v[32:35]
	v_mfma_f32_16x16x32_bf16 v[20:23], v[206:209], v[178:181], v[20:23]
	v_mfma_f32_16x16x32_bf16 v[16:19], v[214:217], v[178:181], v[16:19]
	v_mfma_f32_16x16x32_bf16 v[4:7], v[206:209], v[186:189], v[4:7]
	v_mfma_f32_16x16x32_bf16 v[0:3], v[214:217], v[186:189], v[0:3]
	s_add_u32 s26, s26, 0x100
	s_addc_u32 s27, s27, 0
	s_cmp_ge_i32 s46, s44
	s_mov_b32 s28, s46
	s_barrier
	s_cbranch_scc0 .LBB0_400

; #define PG8_STAGE(bufoff, gbase, voff) do { _Pragma("unroll") for (int _i = 0; _i < 2; ++_i) \
;         __builtin_amdgcn_global_load_lds((const unsigned*)((const char*)(gbase) + (voff)[_i]), (LAS unsigned*)(lds + (bufoff) + ldsw + _i * 8192), 16, 0, 0); } while (0)
; #define PG8_LDA(dst, b, h) do { _Pragma("unroll") for (int m = 0; m < 4; ++m) _Pragma("unroll") for (int k = 0; k < 2; ++k) dst[m][k] = *(const LAS bf16x8*)(lds + PG8_SA(b, h) + aoff + m * 2048 + k * 1024); } while (0)
; #define PG8_LDB(dst, b, h) do { _Pragma("unroll") for (int n = 0; n < 2; ++n) _Pragma("unroll") for (int k = 0; k < 2; ++k) dst[n][k] = *(const LAS bf16x8*)(lds + PG8_SB(b, h) + boff + n * 2048 + k * 1024); } while (0)
; #define PG8_MMA(ai, bj, At, Bt) do { __builtin_amdgcn_s_setprio(1); _Pragma("unroll") for (int m = 0; m < 4; ++m) _Pragma("unroll") for (int n = 0; n < 2; ++n) _Pragma("unroll") for (int k = 0; k < 2; ++k) \
;         acc[ai][bj][m][n] = __builtin_amdgcn_mfma_f32_16x16x32_bf16(Bt[n][k], At[m][k], acc[ai][bj][m][n], 0, 0, 0); __builtin_amdgcn_s_setprio(0); } while (0)
; #define PG8_WAIT_L(n) asm volatile("s_waitcnt lgkmcnt(" #n ")" ::: "memory")
; #define PG8_BAR __builtin_amdgcn_s_barrier()
; #define PG8_SCHED __builtin_amdgcn_sched_barrier(0)
; template <class Epi>
; __device__ __forceinline__ void gemm_phase(LAS unsigned char* lds, const Gemm g, const StaticOrder& S, const Epi& E) {
;     ...
;             PG8_LDB(B0, 0, 0); PG8_SCHED; PG8_LDA(At, 0, 0); PG8_STAGE(PG8_SA(1, 1), a1 + hstep, voffA);
;             PG8_WAIT_L(8); PG8_BAR; PG8_WAIT_L(0); PG8_MMA(0, 0, At, B0); PG8_BAR; PG8_SCHED;
;             PG8_LDB(B1, 0, 1); PG8_STAGE(PG8_SB(0, 0), b2, voffB);
;             PG8_BAR; PG8_WAIT_L(0); PG8_MMA(0, 1, At, B1); PG8_BAR;
;             PG8_LDA(At, 0, 1); PG8_STAGE(PG8_SA(0, 0), a2, voffA);
;             PG8_BAR; PG8_WAIT_L(0); PG8_MMA(1, 0, At, B0); PG8_BAR; PG8_SCHED;
.LBB0_419:
	s_add_i32 s60, s36, 2
	s_add_u32 s38, s34, 0x80
	s_addc_u32 s37, s35, 0
	s_add_i32 s61, 0, 0x10000
	v_add_u32_e32 v140, s61, v245
	ds_read_b128 v[128:131], v140
	ds_read_b128 v[132:135], v140 offset:1024
	ds_read_b128 v[136:139], v140 offset:2048
	ds_read_b128 v[140:143], v140 offset:3072
	s_cmp_eq_u32 s52, s36
	s_cselect_b32 s36, s28, s38
	s_cselect_b32 s37, s29, s37
	s_cselect_b32 s39, s31, s59
	s_cselect_b32 s38, s30, s58
	v_lshl_add_u64 v[176:177], s[34:35], 0, v[218:219]
	s_add_i32 m0, s45, 0xc000
	ds_read_b128 v[144:147], v246
	ds_read_b128 v[148:151], v246 offset:1024
	ds_read_b128 v[152:155], v246 offset:2048
	ds_read_b128 v[156:159], v246 offset:3072
	ds_read_b128 v[160:163], v246 offset:4096
	ds_read_b128 v[164:167], v246 offset:5120
	ds_read_b128 v[168:171], v246 offset:6144
	ds_read_b128 v[172:175], v246 offset:7168
	global_load_lds_dwordx4 v[176:177], off
	v_lshl_add_u64 v[176:177], s[34:35], 0, v[216:217]
	s_add_i32 m0, s45, 0xe000
	s_nop 0
	global_load_lds_dwordx4 v[176:177], off
	s_waitcnt lgkmcnt(8)
	s_barrier
	s_waitcnt lgkmcnt(0)
	s_waitcnt lgkmcnt(0)
	v_mfma_f32_16x16x32_bf16 v[124:127], v[128:131], v[144:147], v[124:127]
	v_mfma_f32_16x16x32_bf16 v[120:123], v[136:139], v[144:147], v[120:123]
	v_mfma_f32_16x16x32_bf16 v[108:111], v[128:131], v[152:155], v[108:111]
	v_mfma_f32_16x16x32_bf16 v[104:107], v[136:139], v[152:155], v[104:107]
	v_mfma_f32_16x16x32_bf16 v[92:95], v[128:131], v[160:163], v[92:95]
	v_mfma_f32_16x16x32_bf16 v[88:91], v[136:139], v[160:163], v[88:91]
	v_mfma_f32_16x16x32_bf16 v[76:79], v[128:131], v[168:171], v[76:79]
	v_mfma_f32_16x16x32_bf16 v[72:75], v[136:139], v[168:171], v[72:75]
	v_mfma_f32_16x16x32_bf16 v[124:127], v[132:135], v[148:151], v[124:127]
	v_mfma_f32_16x16x32_bf16 v[120:123], v[140:143], v[148:151], v[120:123]
	v_mfma_f32_16x16x32_bf16 v[108:111], v[132:135], v[156:159], v[108:111]
	v_mfma_f32_16x16x32_bf16 v[104:107], v[140:143], v[156:159], v[104:107]
	v_mfma_f32_16x16x32_bf16 v[92:95], v[132:135], v[164:167], v[92:95]
	v_mfma_f32_16x16x32_bf16 v[88:91], v[140:143], v[164:167], v[88:91]
	v_mfma_f32_16x16x32_bf16 v[76:79], v[132:135], v[172:175], v[76:79]
	v_mfma_f32_16x16x32_bf16 v[72:75], v[140:143], v[172:175], v[72:75]
	s_barrier
	s_add_i32 s62, 0, 0x14000
	s_add_i32 s61, s61, s43
	v_add_u32_e32 v188, s62, v245
	v_lshl_add_u64 v[220:221], s[38:39], 0, v[194:195]
	s_mov_b32 m0, s61
	ds_read_b128 v[176:179], v188
	ds_read_b128 v[180:183], v188 offset:1024
	ds_read_b128 v[184:187], v188 offset:2048
	ds_read_b128 v[188:191], v188 offset:3072
	global_load_lds_dwordx4 v[220:221], off
	v_lshl_add_u64 v[222:223], s[38:39], 0, v[206:207]
	s_add_i32 m0, s61, 0x2000
	s_nop 0
	global_load_lds_dwordx4 v[222:223], off
	s_barrier
	s_waitcnt lgkmcnt(0)
	s_waitcnt lgkmcnt(0)
	v_mfma_f32_16x16x32_bf16 v[116:119], v[176:179], v[144:147], v[116:119]
	v_mfma_f32_16x16x32_bf16 v[112:115], v[184:187], v[144:147], v[112:115]
	v_mfma_f32_16x16x32_bf16 v[100:103], v[176:179], v[152:155], v[100:103]
	v_mfma_f32_16x16x32_bf16 v[96:99], v[184:187], v[152:155], v[96:99]
	v_mfma_f32_16x16x32_bf16 v[84:87], v[176:179], v[160:163], v[84:87]
	v_mfma_f32_16x16x32_bf16 v[80:83], v[184:187], v[160:163], v[80:83]
	v_mfma_f32_16x16x32_bf16 v[68:71], v[176:179], v[168:171], v[68:71]
	v_mfma_f32_16x16x32_bf16 v[64:67], v[184:187], v[168:171], v[64:67]
	v_mfma_f32_16x16x32_bf16 v[116:119], v[180:183], v[148:151], v[116:119]
	v_mfma_f32_16x16x32_bf16 v[112:115], v[188:191], v[148:151], v[112:115]
	v_mfma_f32_16x16x32_bf16 v[100:103], v[180:183], v[156:159], v[100:103]
	v_mfma_f32_16x16x32_bf16 v[96:99], v[188:191], v[156:159], v[96:99]
	v_mfma_f32_16x16x32_bf16 v[84:87], v[180:183], v[164:167], v[84:87]
	v_mfma_f32_16x16x32_bf16 v[80:83], v[188:191], v[164:167], v[80:83]
	v_mfma_f32_16x16x32_bf16 v[68:71], v[180:183], v[172:175], v[68:71]
	v_mfma_f32_16x16x32_bf16 v[64:67], v[188:191], v[172:175], v[64:67]
	s_mov_b32 m0, s45
	v_lshl_add_u64 v[224:225], s[36:37], 0, v[202:203]
	s_barrier
	ds_read_b128 v[144:147], v246 offset:16384
	ds_read_b128 v[148:151], v246 offset:17408
	ds_read_b128 v[152:155], v246 offset:18432
	ds_read_b128 v[156:159], v246 offset:19456
	ds_read_b128 v[160:163], v246 offset:20480
	ds_read_b128 v[164:167], v246 offset:21504
	ds_read_b128 v[168:171], v246 offset:22528
	ds_read_b128 v[172:175], v246 offset:23552
	global_load_lds_dwordx4 v[224:225], off
	v_lshl_add_u64 v[226:227], s[36:37], 0, v[204:205]
	s_mov_b32 m0, s46
	s_nop 0
	global_load_lds_dwordx4 v[226:227], off
	s_barrier
	s_waitcnt lgkmcnt(0)
	s_waitcnt lgkmcnt(0)
	v_mfma_f32_16x16x32_bf16 v[60:63], v[128:131], v[144:147], v[60:63]
	v_mfma_f32_16x16x32_bf16 v[56:59], v[136:139], v[144:147], v[56:59]
	v_mfma_f32_16x16x32_bf16 v[44:47], v[128:131], v[152:155], v[44:47]
	v_mfma_f32_16x16x32_bf16 v[40:43], v[136:139], v[152:155], v[40:43]
	v_mfma_f32_16x16x32_bf16 v[28:31], v[128:131], v[160:163], v[28:31]
	v_mfma_f32_16x16x32_bf16 v[24:27], v[136:139], v[160:163], v[24:27]
	v_mfma_f32_16x16x32_bf16 v[12:15], v[128:131], v[168:171], v[12:15]
	v_mfma_f32_16x16x32_bf16 v[8:11], v[136:139], v[168:171], v[8:11]
	v_mfma_f32_16x16x32_bf16 v[60:63], v[132:135], v[148:151], v[60:63]
	v_mfma_f32_16x16x32_bf16 v[56:59], v[140:143], v[148:151], v[56:59]
	v_mfma_f32_16x16x32_bf16 v[44:47], v[132:135], v[156:159], v[44:47]
	v_mfma_f32_16x16x32_bf16 v[40:43], v[140:143], v[156:159], v[40:43]
	v_mfma_f32_16x16x32_bf16 v[28:31], v[132:135], v[164:167], v[28:31]
	v_mfma_f32_16x16x32_bf16 v[24:27], v[140:143], v[164:167], v[24:27]
	v_mfma_f32_16x16x32_bf16 v[12:15], v[132:135], v[172:175], v[12:15]
	v_mfma_f32_16x16x32_bf16 v[8:11], v[140:143], v[172:175], v[8:11]
	s_barrier
; #define PG8_STAGE(bufoff, gbase, voff) do { _Pragma("unroll") for (int _i = 0; _i < 2; ++_i) \
;         __builtin_amdgcn_global_load_lds((const unsigned*)((const char*)(gbase) + (voff)[_i]), (LAS unsigned*)(lds + (bufoff) + ldsw + _i * 8192), 16, 0, 0); } while (0)
; #define PG8_LDA(dst, b, h) do { _Pragma("unroll") for (int m = 0; m < 4; ++m) _Pragma("unroll") for (int k = 0; k < 2; ++k) dst[m][k] = *(const LAS bf16x8*)(lds + PG8_SA(b, h) + aoff + m * 2048 + k * 1024); } while (0)
; #define PG8_LDB(dst, b, h) do { _Pragma("unroll") for (int n = 0; n < 2; ++n) _Pragma("unroll") for (int k = 0; k < 2; ++k) dst[n][k] = *(const LAS bf16x8*)(lds + PG8_SB(b, h) + boff + n * 2048 + k * 1024); } while (0)
; #define PG8_MMA(ai, bj, At, Bt) do { __builtin_amdgcn_s_setprio(1); _Pragma("unroll") for (int m = 0; m < 4; ++m) _Pragma("unroll") for (int n = 0; n < 2; ++n) _Pragma("unroll") for (int k = 0; k < 2; ++k) \
;         acc[ai][bj][m][n] = __builtin_amdgcn_mfma_f32_16x16x32_bf16(Bt[n][k], At[m][k], acc[ai][bj][m][n], 0, 0, 0); __builtin_amdgcn_s_setprio(0); } while (0)
; #define PG8_WAIT_V(n) asm volatile("s_waitcnt vmcnt(" #n ")" ::: "memory")
; #define PG8_WAIT_L(n) asm volatile("s_waitcnt lgkmcnt(" #n ")" ::: "memory")
; #define PG8_BAR __builtin_amdgcn_s_barrier()
; #define PG8_SCHED __builtin_amdgcn_sched_barrier(0)
; template <class Epi>
; __device__ __forceinline__ void gemm_phase(LAS unsigned char* lds, const Gemm g, const StaticOrder& S, const Epi& E) {
;     ...
;             PG8_STAGE(PG8_SB(0, 1), b2 + hstep, voffB);
;             PG8_WAIT_V(6); PG8_BAR; PG8_MMA(1, 1, At, B1); PG8_BAR;
;             PG8_LDB(B0, 1, 0); PG8_SCHED; PG8_LDA(At, 1, 0); PG8_STAGE(PG8_SA(0, 1), a2 + hstep, voffA);
;             PG8_WAIT_L(8); PG8_BAR; PG8_WAIT_L(0); PG8_MMA(0, 0, At, B0); PG8_BAR; PG8_SCHED;
;             PG8_LDB(B1, 1, 1); PG8_STAGE(PG8_SB(1, 0), b3, voffB);
	s_add_u32 s38, s38, s4
	s_addc_u32 s39, s39, s5
	s_add_i32 s61, s62, s43
	v_lshl_add_u64 v[228:229], s[38:39], 0, v[194:195]
	s_mov_b32 m0, s61
	v_lshl_add_u64 v[230:231], s[38:39], 0, v[206:207]
	global_load_lds_dwordx4 v[228:229], off
	s_add_i32 m0, s61, 0x2000
	s_nop 0
	global_load_lds_dwordx4 v[230:231], off
	s_waitcnt vmcnt(6)
	s_barrier
	v_mfma_f32_16x16x32_bf16 v[52:55], v[176:179], v[144:147], v[52:55]
	v_mfma_f32_16x16x32_bf16 v[48:51], v[184:187], v[144:147], v[48:51]
	v_mfma_f32_16x16x32_bf16 v[36:39], v[176:179], v[152:155], v[36:39]
	v_mfma_f32_16x16x32_bf16 v[32:35], v[184:187], v[152:155], v[32:35]
	v_mfma_f32_16x16x32_bf16 v[20:23], v[176:179], v[160:163], v[20:23]
	v_mfma_f32_16x16x32_bf16 v[16:19], v[184:187], v[160:163], v[16:19]
	v_mfma_f32_16x16x32_bf16 v[4:7], v[176:179], v[168:171], v[4:7]
	v_mfma_f32_16x16x32_bf16 v[0:3], v[184:187], v[168:171], v[0:3]
	v_mfma_f32_16x16x32_bf16 v[52:55], v[180:183], v[148:151], v[52:55]
	v_mfma_f32_16x16x32_bf16 v[48:51], v[188:191], v[148:151], v[48:51]
	v_mfma_f32_16x16x32_bf16 v[36:39], v[180:183], v[156:159], v[36:39]
	v_mfma_f32_16x16x32_bf16 v[32:35], v[188:191], v[156:159], v[32:35]
	v_mfma_f32_16x16x32_bf16 v[20:23], v[180:183], v[164:167], v[20:23]
	v_mfma_f32_16x16x32_bf16 v[16:19], v[188:191], v[164:167], v[16:19]
	v_mfma_f32_16x16x32_bf16 v[4:7], v[180:183], v[172:175], v[4:7]
	v_mfma_f32_16x16x32_bf16 v[0:3], v[188:191], v[172:175], v[0:3]
	s_add_i32 s38, 0, 0x18000
	v_add_u32_e32 v140, s38, v245
	s_barrier
	ds_read_b128 v[128:131], v140
	ds_read_b128 v[132:135], v140 offset:1024
	ds_read_b128 v[136:139], v140 offset:2048
	ds_read_b128 v[140:143], v140 offset:3072
	s_add_u32 s36, s36, s4
	s_addc_u32 s37, s37, s5
	s_mov_b32 m0, s47
	v_lshl_add_u64 v[176:177], s[36:37], 0, v[202:203]
	ds_read_b128 v[144:147], v246 offset:32768
	ds_read_b128 v[148:151], v246 offset:33792
	ds_read_b128 v[152:155], v246 offset:34816
	ds_read_b128 v[156:159], v246 offset:35840
	ds_read_b128 v[160:163], v246 offset:36864
	ds_read_b128 v[164:167], v246 offset:37888
	ds_read_b128 v[168:171], v246 offset:38912
	ds_read_b128 v[172:175], v246 offset:39936
	global_load_lds_dwordx4 v[176:177], off
	v_lshl_add_u64 v[176:177], s[36:37], 0, v[204:205]
	s_mov_b32 m0, s48
	s_nop 0
	global_load_lds_dwordx4 v[176:177], off
	s_waitcnt lgkmcnt(8)
	s_barrier
	s_waitcnt lgkmcnt(0)
	s_waitcnt lgkmcnt(0)
	v_mfma_f32_16x16x32_bf16 v[124:127], v[128:131], v[144:147], v[124:127]
	v_mfma_f32_16x16x32_bf16 v[120:123], v[136:139], v[144:147], v[120:123]
	v_mfma_f32_16x16x32_bf16 v[108:111], v[128:131], v[152:155], v[108:111]
	v_mfma_f32_16x16x32_bf16 v[104:107], v[136:139], v[152:155], v[104:107]
	v_mfma_f32_16x16x32_bf16 v[92:95], v[128:131], v[160:163], v[92:95]
	v_mfma_f32_16x16x32_bf16 v[88:91], v[136:139], v[160:163], v[88:91]
	v_mfma_f32_16x16x32_bf16 v[76:79], v[128:131], v[168:171], v[76:79]
	v_mfma_f32_16x16x32_bf16 v[72:75], v[136:139], v[168:171], v[72:75]
	v_mfma_f32_16x16x32_bf16 v[124:127], v[132:135], v[148:151], v[124:127]
	v_mfma_f32_16x16x32_bf16 v[120:123], v[140:143], v[148:151], v[120:123]
	v_mfma_f32_16x16x32_bf16 v[108:111], v[132:135], v[156:159], v[108:111]
	v_mfma_f32_16x16x32_bf16 v[104:107], v[140:143], v[156:159], v[104:107]
	v_mfma_f32_16x16x32_bf16 v[92:95], v[132:135], v[164:167], v[92:95]
	v_mfma_f32_16x16x32_bf16 v[88:91], v[140:143], v[164:167], v[88:91]
	v_mfma_f32_16x16x32_bf16 v[76:79], v[132:135], v[172:175], v[76:79]
	v_mfma_f32_16x16x32_bf16 v[72:75], v[140:143], v[172:175], v[72:75]
	s_barrier
	s_add_i32 s36, 0, 0x1c000
	s_add_i32 s37, s38, s43
	v_add_u32_e32 v188, s36, v245
	v_lshl_add_u64 v[220:221], v[220:221], 0, s[64:65]
	s_mov_b32 m0, s37
	ds_read_b128 v[176:179], v188
	ds_read_b128 v[180:183], v188 offset:1024
	ds_read_b128 v[184:187], v188 offset:2048
	ds_read_b128 v[188:191], v188 offset:3072
	global_load_lds_dwordx4 v[220:221], off
	v_lshl_add_u64 v[220:221], v[222:223], 0, s[64:65]
	s_add_i32 m0, s37, 0x2000
	s_nop 0
	global_load_lds_dwordx4 v[220:221], off
	s_barrier
; #define PG8_STAGE(bufoff, gbase, voff) do { _Pragma("unroll") for (int _i = 0; _i < 2; ++_i) \
;         __builtin_amdgcn_global_load_lds((const unsigned*)((const char*)(gbase) + (voff)[_i]), (LAS unsigned*)(lds + (bufoff) + ldsw + _i * 8192), 16, 0, 0); } while (0)
; #define PG8_LDA(dst, b, h) do { _Pragma("unroll") for (int m = 0; m < 4; ++m) _Pragma("unroll") for (int k = 0; k < 2; ++k) dst[m][k] = *(const LAS bf16x8*)(lds + PG8_SA(b, h) + aoff + m * 2048 + k * 1024); } while (0)
; #define PG8_LDB(dst, b, h) do { _Pragma("unroll") for (int n = 0; n < 2; ++n) _Pragma("unroll") for (int k = 0; k < 2; ++k) dst[n][k] = *(const LAS bf16x8*)(lds + PG8_SB(b, h) + boff + n * 2048 + k * 1024); } while (0)
; #define PG8_MMA(ai, bj, At, Bt) do { __builtin_amdgcn_s_setprio(1); _Pragma("unroll") for (int m = 0; m < 4; ++m) _Pragma("unroll") for (int n = 0; n < 2; ++n) _Pragma("unroll") for (int k = 0; k < 2; ++k) \
;         acc[ai][bj][m][n] = __builtin_amdgcn_mfma_f32_16x16x32_bf16(Bt[n][k], At[m][k], acc[ai][bj][m][n], 0, 0, 0); __builtin_amdgcn_s_setprio(0); } while (0)
; #define PG8_WAIT_V(n) asm volatile("s_waitcnt vmcnt(" #n ")" ::: "memory")
; #define PG8_WAIT_L(n) asm volatile("s_waitcnt lgkmcnt(" #n ")" ::: "memory")
; #define PG8_BAR __builtin_amdgcn_s_barrier()
; #define PG8_SCHED __builtin_amdgcn_sched_barrier(0)
; template <class Epi>
; __device__ __forceinline__ void gemm_phase(LAS unsigned char* lds, const Gemm g, const StaticOrder& S, const Epi& E) {
;     ...
;             PG8_LDB(B1, 1, 1); PG8_STAGE(PG8_SB(1, 0), b3, voffB);
;             PG8_BAR; PG8_WAIT_L(0); PG8_MMA(0, 1, At, B1); PG8_BAR;
;             PG8_LDA(At, 1, 1); PG8_STAGE(PG8_SA(1, 0), a3, voffA);
;             PG8_BAR; PG8_WAIT_L(0); PG8_MMA(1, 0, At, B0); PG8_BAR; PG8_SCHED;
;             PG8_STAGE(PG8_SB(1, 1), b3 + hstep, voffB);
;             PG8_WAIT_V(6); PG8_BAR; PG8_MMA(1, 1, At, B1); PG8_BAR;
;         }
	s_waitcnt lgkmcnt(0)
	s_waitcnt lgkmcnt(0)
	v_mfma_f32_16x16x32_bf16 v[116:119], v[176:179], v[144:147], v[116:119]
	v_mfma_f32_16x16x32_bf16 v[112:115], v[184:187], v[144:147], v[112:115]
	v_mfma_f32_16x16x32_bf16 v[100:103], v[176:179], v[152:155], v[100:103]
	v_mfma_f32_16x16x32_bf16 v[96:99], v[184:187], v[152:155], v[96:99]
	v_mfma_f32_16x16x32_bf16 v[84:87], v[176:179], v[160:163], v[84:87]
	v_mfma_f32_16x16x32_bf16 v[80:83], v[184:187], v[160:163], v[80:83]
	v_mfma_f32_16x16x32_bf16 v[68:71], v[176:179], v[168:171], v[68:71]
	v_mfma_f32_16x16x32_bf16 v[64:67], v[184:187], v[168:171], v[64:67]
	v_mfma_f32_16x16x32_bf16 v[116:119], v[180:183], v[148:151], v[116:119]
	v_mfma_f32_16x16x32_bf16 v[112:115], v[188:191], v[148:151], v[112:115]
	v_mfma_f32_16x16x32_bf16 v[100:103], v[180:183], v[156:159], v[100:103]
	v_mfma_f32_16x16x32_bf16 v[96:99], v[188:191], v[156:159], v[96:99]
	v_mfma_f32_16x16x32_bf16 v[84:87], v[180:183], v[164:167], v[84:87]
	v_mfma_f32_16x16x32_bf16 v[80:83], v[188:191], v[164:167], v[80:83]
	v_mfma_f32_16x16x32_bf16 v[68:71], v[180:183], v[172:175], v[68:71]
	v_mfma_f32_16x16x32_bf16 v[64:67], v[188:191], v[172:175], v[64:67]
	s_mov_b32 m0, s49
	v_lshl_add_u64 v[220:221], v[224:225], 0, s[64:65]
	s_barrier
	ds_read_b128 v[144:147], v246 offset:49152
	ds_read_b128 v[148:151], v246 offset:50176
	ds_read_b128 v[152:155], v246 offset:51200
	ds_read_b128 v[156:159], v246 offset:52224
	ds_read_b128 v[160:163], v246 offset:53248
	ds_read_b128 v[164:167], v246 offset:54272
	ds_read_b128 v[168:171], v246 offset:55296
	ds_read_b128 v[172:175], v246 offset:56320
	global_load_lds_dwordx4 v[220:221], off
	v_lshl_add_u64 v[220:221], v[226:227], 0, s[64:65]
	s_mov_b32 m0, s50
	s_nop 0
	global_load_lds_dwordx4 v[220:221], off
	s_barrier
	s_waitcnt lgkmcnt(0)
	s_waitcnt lgkmcnt(0)
	v_mfma_f32_16x16x32_bf16 v[60:63], v[128:131], v[144:147], v[60:63]
	v_mfma_f32_16x16x32_bf16 v[56:59], v[136:139], v[144:147], v[56:59]
	v_mfma_f32_16x16x32_bf16 v[44:47], v[128:131], v[152:155], v[44:47]
	v_mfma_f32_16x16x32_bf16 v[40:43], v[136:139], v[152:155], v[40:43]
	v_mfma_f32_16x16x32_bf16 v[28:31], v[128:131], v[160:163], v[28:31]
	v_mfma_f32_16x16x32_bf16 v[24:27], v[136:139], v[160:163], v[24:27]
	v_mfma_f32_16x16x32_bf16 v[12:15], v[128:131], v[168:171], v[12:15]
	v_mfma_f32_16x16x32_bf16 v[8:11], v[136:139], v[168:171], v[8:11]
	v_mfma_f32_16x16x32_bf16 v[60:63], v[132:135], v[148:151], v[60:63]
	v_mfma_f32_16x16x32_bf16 v[56:59], v[140:143], v[148:151], v[56:59]
	v_mfma_f32_16x16x32_bf16 v[44:47], v[132:135], v[156:159], v[44:47]
	v_mfma_f32_16x16x32_bf16 v[40:43], v[140:143], v[156:159], v[40:43]
	v_mfma_f32_16x16x32_bf16 v[28:31], v[132:135], v[164:167], v[28:31]
	v_mfma_f32_16x16x32_bf16 v[24:27], v[140:143], v[164:167], v[24:27]
	v_mfma_f32_16x16x32_bf16 v[12:15], v[132:135], v[172:175], v[12:15]
	v_mfma_f32_16x16x32_bf16 v[8:11], v[140:143], v[172:175], v[8:11]
	s_barrier
	s_add_i32 s36, s36, s43
	v_lshl_add_u64 v[128:129], v[228:229], 0, s[64:65]
	s_mov_b32 m0, s36
	s_nop 0
	global_load_lds_dwordx4 v[128:129], off
	v_lshl_add_u64 v[128:129], v[230:231], 0, s[64:65]
	s_add_i32 m0, s36, 0x2000
	s_nop 0
	global_load_lds_dwordx4 v[128:129], off
	s_waitcnt vmcnt(6)
	s_barrier
	v_mfma_f32_16x16x32_bf16 v[52:55], v[176:179], v[144:147], v[52:55]
	v_mfma_f32_16x16x32_bf16 v[48:51], v[184:187], v[144:147], v[48:51]
	v_mfma_f32_16x16x32_bf16 v[36:39], v[176:179], v[152:155], v[36:39]
	v_mfma_f32_16x16x32_bf16 v[32:35], v[184:187], v[152:155], v[32:35]
	v_mfma_f32_16x16x32_bf16 v[20:23], v[176:179], v[160:163], v[20:23]
	v_mfma_f32_16x16x32_bf16 v[16:19], v[184:187], v[160:163], v[16:19]
	v_mfma_f32_16x16x32_bf16 v[4:7], v[176:179], v[168:171], v[4:7]
	v_mfma_f32_16x16x32_bf16 v[0:3], v[184:187], v[168:171], v[0:3]
	v_mfma_f32_16x16x32_bf16 v[52:55], v[180:183], v[148:151], v[52:55]
	v_mfma_f32_16x16x32_bf16 v[48:51], v[188:191], v[148:151], v[48:51]
	v_mfma_f32_16x16x32_bf16 v[36:39], v[180:183], v[156:159], v[36:39]
	v_mfma_f32_16x16x32_bf16 v[32:35], v[188:191], v[156:159], v[32:35]
	v_mfma_f32_16x16x32_bf16 v[20:23], v[180:183], v[164:167], v[20:23]
	v_mfma_f32_16x16x32_bf16 v[16:19], v[188:191], v[164:167], v[16:19]
	v_mfma_f32_16x16x32_bf16 v[4:7], v[180:183], v[172:175], v[4:7]
	v_mfma_f32_16x16x32_bf16 v[0:3], v[188:191], v[172:175], v[0:3]
	s_add_u32 s58, s58, 0x100
	s_addc_u32 s59, s59, 0
	s_add_u32 s34, s34, 0x100
	s_addc_u32 s35, s35, 0
	s_cmp_ge_i32 s60, s51
	s_mov_b32 s36, s60
	s_barrier
	s_cbranch_scc0 .LBB0_419

; #define PG8_STAGE(bufoff, gbase, voff) do { _Pragma("unroll") for (int _i = 0; _i < 2; ++_i) \
;         __builtin_amdgcn_global_load_lds((const unsigned*)((const char*)(gbase) + (voff)[_i]), (LAS unsigned*)(lds + (bufoff) + ldsw + _i * 8192), 16, 0, 0); } while (0)
; #define PG8_LDA(dst, b, h) do { _Pragma("unroll") for (int m = 0; m < 4; ++m) _Pragma("unroll") for (int k = 0; k < 2; ++k) dst[m][k] = *(const LAS bf16x8*)(lds + PG8_SA(b, h) + aoff + m * 2048 + k * 1024); } while (0)
; #define PG8_LDB(dst, b, h) do { _Pragma("unroll") for (int n = 0; n < 2; ++n) _Pragma("unroll") for (int k = 0; k < 2; ++k) dst[n][k] = *(const LAS bf16x8*)(lds + PG8_SB(b, h) + boff + n * 2048 + k * 1024); } while (0)
; #define PG8_MMA(ai, bj, At, Bt) do { __builtin_amdgcn_s_setprio(1); _Pragma("unroll") for (int m = 0; m < 4; ++m) _Pragma("unroll") for (int n = 0; n < 2; ++n) _Pragma("unroll") for (int k = 0; k < 2; ++k) \
;         acc[ai][bj][m][n] = __builtin_amdgcn_mfma_f32_16x16x32_bf16(Bt[n][k], At[m][k], acc[ai][bj][m][n], 0, 0, 0); __builtin_amdgcn_s_setprio(0); } while (0)
; #define PG8_WAIT_L(n) asm volatile("s_waitcnt lgkmcnt(" #n ")" ::: "memory")
; #define PG8_BAR __builtin_amdgcn_s_barrier()
; #define PG8_SCHED __builtin_amdgcn_sched_barrier(0)
; template <class Epi>
; __device__ __forceinline__ void gemm_phase(LAS unsigned char* lds, const Gemm g, const StaticOrder& S, const Epi& E) {
;     ...
;             PG8_LDB(B0, 0, 0); PG8_SCHED; PG8_LDA(At, 0, 0); PG8_STAGE(PG8_SA(1, 1), a1 + hstep, voffA);
;             PG8_WAIT_L(8); PG8_BAR; PG8_WAIT_L(0); PG8_MMA(0, 0, At, B0); PG8_BAR; PG8_SCHED;
;             PG8_LDB(B1, 0, 1); PG8_STAGE(PG8_SB(0, 0), b2, voffB);
;             PG8_BAR; PG8_WAIT_L(0); PG8_MMA(0, 1, At, B1); PG8_BAR;
;             PG8_LDA(At, 0, 1); PG8_STAGE(PG8_SA(0, 0), a2, voffA);
;             PG8_BAR; PG8_WAIT_L(0); PG8_MMA(1, 0, At, B0); PG8_BAR; PG8_SCHED;
.LBB0_433:
	s_add_i32 s48, s30, 2
	s_add_u32 s28, s26, 0x100
	s_addc_u32 s29, s27, 0
	s_cmp_lg_u32 s47, s30
	s_cselect_b32 s34, s28, 0
	s_cselect_b32 s35, s29, 0
	s_add_u32 s30, s24, s34
	s_addc_u32 s31, s25, s35
	s_add_i32 s49, 0, 0x10000
	v_add_u32_e32 v154, s49, v140
	ds_read_b128 v[142:145], v154
	ds_read_b128 v[146:149], v154 offset:1024
	ds_read_b128 v[150:153], v154 offset:2048
	ds_read_b128 v[154:157], v154 offset:3072
	s_add_u32 s34, s6, s34
	s_addc_u32 s35, s7, s35
	v_lshl_add_u64 v[190:191], v[136:137], 0, s[26:27]
	s_add_i32 m0, s40, 0xc000
	ds_read_b128 v[158:161], v141
	ds_read_b128 v[162:165], v141 offset:1024
	ds_read_b128 v[166:169], v141 offset:2048
	ds_read_b128 v[170:173], v141 offset:3072
	ds_read_b128 v[174:177], v141 offset:4096
	ds_read_b128 v[178:181], v141 offset:5120
	ds_read_b128 v[182:185], v141 offset:6144
	ds_read_b128 v[186:189], v141 offset:7168
	global_load_lds_dwordx4 v[190:191], off
	v_lshl_add_u64 v[190:191], v[134:135], 0, s[26:27]
	s_add_i32 m0, s40, 0xe000
	s_nop 0
	global_load_lds_dwordx4 v[190:191], off
	s_waitcnt lgkmcnt(8)
	s_barrier
	s_waitcnt lgkmcnt(0)
	s_waitcnt lgkmcnt(0)
	v_mfma_f32_16x16x32_bf16 v[124:127], v[142:145], v[158:161], v[124:127]
	v_mfma_f32_16x16x32_bf16 v[120:123], v[150:153], v[158:161], v[120:123]
	v_mfma_f32_16x16x32_bf16 v[108:111], v[142:145], v[166:169], v[108:111]
	v_mfma_f32_16x16x32_bf16 v[104:107], v[150:153], v[166:169], v[104:107]
	v_mfma_f32_16x16x32_bf16 v[92:95], v[142:145], v[174:177], v[92:95]
	v_mfma_f32_16x16x32_bf16 v[88:91], v[150:153], v[174:177], v[88:91]
	v_mfma_f32_16x16x32_bf16 v[76:79], v[142:145], v[182:185], v[76:79]
	v_mfma_f32_16x16x32_bf16 v[72:75], v[150:153], v[182:185], v[72:75]
	v_mfma_f32_16x16x32_bf16 v[124:127], v[146:149], v[162:165], v[124:127]
	v_mfma_f32_16x16x32_bf16 v[120:123], v[154:157], v[162:165], v[120:123]
	v_mfma_f32_16x16x32_bf16 v[108:111], v[146:149], v[170:173], v[108:111]
	v_mfma_f32_16x16x32_bf16 v[104:107], v[154:157], v[170:173], v[104:107]
	v_mfma_f32_16x16x32_bf16 v[92:95], v[146:149], v[178:181], v[92:95]
	v_mfma_f32_16x16x32_bf16 v[88:91], v[154:157], v[178:181], v[88:91]
	v_mfma_f32_16x16x32_bf16 v[76:79], v[146:149], v[186:189], v[76:79]
	v_mfma_f32_16x16x32_bf16 v[72:75], v[154:157], v[186:189], v[72:75]
	s_barrier
	s_add_i32 s50, 0, 0x14000
	v_add_u32_e32 v190, s50, v140
	s_add_i32 s26, s49, s39
	ds_read_b128 v[202:205], v190
	ds_read_b128 v[206:209], v190 offset:1024
	ds_read_b128 v[210:213], v190 offset:2048
	ds_read_b128 v[214:217], v190 offset:3072
	v_lshl_add_u64 v[190:191], s[34:35], 0, v[194:195]
	s_mov_b32 m0, s26
	v_lshl_add_u64 v[218:219], s[34:35], 0, v[128:129]
	global_load_lds_dwordx4 v[190:191], off
	s_add_i32 m0, s26, 0x2000
	s_nop 0
	global_load_lds_dwordx4 v[218:219], off
	s_barrier
	s_waitcnt lgkmcnt(0)
	s_waitcnt lgkmcnt(0)
	v_mfma_f32_16x16x32_bf16 v[116:119], v[202:205], v[158:161], v[116:119]
	v_mfma_f32_16x16x32_bf16 v[112:115], v[210:213], v[158:161], v[112:115]
	v_mfma_f32_16x16x32_bf16 v[100:103], v[202:205], v[166:169], v[100:103]
	v_mfma_f32_16x16x32_bf16 v[96:99], v[210:213], v[166:169], v[96:99]
	v_mfma_f32_16x16x32_bf16 v[84:87], v[202:205], v[174:177], v[84:87]
	v_mfma_f32_16x16x32_bf16 v[80:83], v[210:213], v[174:177], v[80:83]
	v_mfma_f32_16x16x32_bf16 v[68:71], v[202:205], v[182:185], v[68:71]
	v_mfma_f32_16x16x32_bf16 v[64:67], v[210:213], v[182:185], v[64:67]
	v_mfma_f32_16x16x32_bf16 v[116:119], v[206:209], v[162:165], v[116:119]
	v_mfma_f32_16x16x32_bf16 v[112:115], v[214:217], v[162:165], v[112:115]
	v_mfma_f32_16x16x32_bf16 v[100:103], v[206:209], v[170:173], v[100:103]
	v_mfma_f32_16x16x32_bf16 v[96:99], v[214:217], v[170:173], v[96:99]
	v_mfma_f32_16x16x32_bf16 v[84:87], v[206:209], v[178:181], v[84:87]
	v_mfma_f32_16x16x32_bf16 v[80:83], v[214:217], v[178:181], v[80:83]
	v_mfma_f32_16x16x32_bf16 v[68:71], v[206:209], v[186:189], v[68:71]
	v_mfma_f32_16x16x32_bf16 v[64:67], v[214:217], v[186:189], v[64:67]
	s_mov_b32 m0, s40
	v_lshl_add_u64 v[220:221], s[30:31], 0, v[132:133]
	s_barrier
	ds_read_b128 v[158:161], v141 offset:16384
	ds_read_b128 v[162:165], v141 offset:17408
	ds_read_b128 v[166:169], v141 offset:18432
	ds_read_b128 v[170:173], v141 offset:19456
	ds_read_b128 v[174:177], v141 offset:20480
	ds_read_b128 v[178:181], v141 offset:21504
	ds_read_b128 v[182:185], v141 offset:22528
	ds_read_b128 v[186:189], v141 offset:23552
	global_load_lds_dwordx4 v[220:221], off
	v_lshl_add_u64 v[222:223], s[30:31], 0, v[130:131]
	s_mov_b32 m0, s41
	s_nop 0
	global_load_lds_dwordx4 v[222:223], off
	s_barrier
	s_waitcnt lgkmcnt(0)
	s_waitcnt lgkmcnt(0)
	v_mfma_f32_16x16x32_bf16 v[60:63], v[142:145], v[158:161], v[60:63]
	v_mfma_f32_16x16x32_bf16 v[56:59], v[150:153], v[158:161], v[56:59]
	v_mfma_f32_16x16x32_bf16 v[44:47], v[142:145], v[166:169], v[44:47]
	v_mfma_f32_16x16x32_bf16 v[40:43], v[150:153], v[166:169], v[40:43]
	v_mfma_f32_16x16x32_bf16 v[28:31], v[142:145], v[174:177], v[28:31]
	v_mfma_f32_16x16x32_bf16 v[24:27], v[150:153], v[174:177], v[24:27]
	v_mfma_f32_16x16x32_bf16 v[12:15], v[142:145], v[182:185], v[12:15]
	v_mfma_f32_16x16x32_bf16 v[8:11], v[150:153], v[182:185], v[8:11]
	v_mfma_f32_16x16x32_bf16 v[60:63], v[146:149], v[162:165], v[60:63]
	v_mfma_f32_16x16x32_bf16 v[56:59], v[154:157], v[162:165], v[56:59]
	v_mfma_f32_16x16x32_bf16 v[44:47], v[146:149], v[170:173], v[44:47]
	v_mfma_f32_16x16x32_bf16 v[40:43], v[154:157], v[170:173], v[40:43]
	v_mfma_f32_16x16x32_bf16 v[28:31], v[146:149], v[178:181], v[28:31]
	v_mfma_f32_16x16x32_bf16 v[24:27], v[154:157], v[178:181], v[24:27]
	v_mfma_f32_16x16x32_bf16 v[12:15], v[146:149], v[186:189], v[12:15]
	v_mfma_f32_16x16x32_bf16 v[8:11], v[154:157], v[186:189], v[8:11]
	s_barrier
; #define PG8_STAGE(bufoff, gbase, voff) do { _Pragma("unroll") for (int _i = 0; _i < 2; ++_i) \
;         __builtin_amdgcn_global_load_lds((const unsigned*)((const char*)(gbase) + (voff)[_i]), (LAS unsigned*)(lds + (bufoff) + ldsw + _i * 8192), 16, 0, 0); } while (0)
; #define PG8_LDA(dst, b, h) do { _Pragma("unroll") for (int m = 0; m < 4; ++m) _Pragma("unroll") for (int k = 0; k < 2; ++k) dst[m][k] = *(const LAS bf16x8*)(lds + PG8_SA(b, h) + aoff + m * 2048 + k * 1024); } while (0)
; #define PG8_LDB(dst, b, h) do { _Pragma("unroll") for (int n = 0; n < 2; ++n) _Pragma("unroll") for (int k = 0; k < 2; ++k) dst[n][k] = *(const LAS bf16x8*)(lds + PG8_SB(b, h) + boff + n * 2048 + k * 1024); } while (0)
; #define PG8_MMA(ai, bj, At, Bt) do { __builtin_amdgcn_s_setprio(1); _Pragma("unroll") for (int m = 0; m < 4; ++m) _Pragma("unroll") for (int n = 0; n < 2; ++n) _Pragma("unroll") for (int k = 0; k < 2; ++k) \
;         acc[ai][bj][m][n] = __builtin_amdgcn_mfma_f32_16x16x32_bf16(Bt[n][k], At[m][k], acc[ai][bj][m][n], 0, 0, 0); __builtin_amdgcn_s_setprio(0); } while (0)
; #define PG8_WAIT_V(n) asm volatile("s_waitcnt vmcnt(" #n ")" ::: "memory")
; #define PG8_WAIT_L(n) asm volatile("s_waitcnt lgkmcnt(" #n ")" ::: "memory")
; #define PG8_BAR __builtin_amdgcn_s_barrier()
; #define PG8_SCHED __builtin_amdgcn_sched_barrier(0)
; template <class Epi>
; __device__ __forceinline__ void gemm_phase(LAS unsigned char* lds, const Gemm g, const StaticOrder& S, const Epi& E) {
;     ...
;             PG8_STAGE(PG8_SB(0, 1), b2 + hstep, voffB);
;             PG8_WAIT_V(6); PG8_BAR; PG8_MMA(1, 1, At, B1); PG8_BAR;
;             PG8_LDB(B0, 1, 0); PG8_SCHED; PG8_LDA(At, 1, 0); PG8_STAGE(PG8_SA(0, 1), a2 + hstep, voffA);
;             PG8_WAIT_L(8); PG8_BAR; PG8_WAIT_L(0); PG8_MMA(0, 0, At, B0); PG8_BAR; PG8_SCHED;
;             PG8_LDB(B1, 1, 1); PG8_STAGE(PG8_SB(1, 0), b3, voffB);
	s_add_u32 s26, s34, s4
	s_addc_u32 s27, s35, s5
	s_add_i32 s34, s50, s39
	v_lshl_add_u64 v[224:225], s[26:27], 0, v[194:195]
	s_mov_b32 m0, s34
	v_lshl_add_u64 v[226:227], s[26:27], 0, v[128:129]
	global_load_lds_dwordx4 v[224:225], off
	s_add_i32 m0, s34, 0x2000
	s_nop 0
	global_load_lds_dwordx4 v[226:227], off
	s_waitcnt vmcnt(6)
	s_barrier
	v_mfma_f32_16x16x32_bf16 v[52:55], v[202:205], v[158:161], v[52:55]
	v_mfma_f32_16x16x32_bf16 v[48:51], v[210:213], v[158:161], v[48:51]
	v_mfma_f32_16x16x32_bf16 v[36:39], v[202:205], v[166:169], v[36:39]
	v_mfma_f32_16x16x32_bf16 v[32:35], v[210:213], v[166:169], v[32:35]
	v_mfma_f32_16x16x32_bf16 v[20:23], v[202:205], v[174:177], v[20:23]
	v_mfma_f32_16x16x32_bf16 v[16:19], v[210:213], v[174:177], v[16:19]
	v_mfma_f32_16x16x32_bf16 v[4:7], v[202:205], v[182:185], v[4:7]
	v_mfma_f32_16x16x32_bf16 v[0:3], v[210:213], v[182:185], v[0:3]
	v_mfma_f32_16x16x32_bf16 v[52:55], v[206:209], v[162:165], v[52:55]
	v_mfma_f32_16x16x32_bf16 v[48:51], v[214:217], v[162:165], v[48:51]
	v_mfma_f32_16x16x32_bf16 v[36:39], v[206:209], v[170:173], v[36:39]
	v_mfma_f32_16x16x32_bf16 v[32:35], v[214:217], v[170:173], v[32:35]
	v_mfma_f32_16x16x32_bf16 v[20:23], v[206:209], v[178:181], v[20:23]
	v_mfma_f32_16x16x32_bf16 v[16:19], v[214:217], v[178:181], v[16:19]
	v_mfma_f32_16x16x32_bf16 v[4:7], v[206:209], v[186:189], v[4:7]
	v_mfma_f32_16x16x32_bf16 v[0:3], v[214:217], v[186:189], v[0:3]
	s_add_i32 s34, 0, 0x18000
	v_add_u32_e32 v154, s34, v140
	s_barrier
	ds_read_b128 v[142:145], v154
	ds_read_b128 v[146:149], v154 offset:1024
	ds_read_b128 v[150:153], v154 offset:2048
	ds_read_b128 v[154:157], v154 offset:3072
	s_add_u32 s26, s30, s4
	s_addc_u32 s27, s31, s5
	s_mov_b32 m0, s42
	v_lshl_add_u64 v[202:203], s[26:27], 0, v[132:133]
	ds_read_b128 v[158:161], v141 offset:32768
	ds_read_b128 v[162:165], v141 offset:33792
	ds_read_b128 v[166:169], v141 offset:34816
	ds_read_b128 v[170:173], v141 offset:35840
	ds_read_b128 v[174:177], v141 offset:36864
	ds_read_b128 v[178:181], v141 offset:37888
	ds_read_b128 v[182:185], v141 offset:38912
	ds_read_b128 v[186:189], v141 offset:39936
	global_load_lds_dwordx4 v[202:203], off
	v_lshl_add_u64 v[202:203], s[26:27], 0, v[130:131]
	s_mov_b32 m0, s43
	s_nop 0
	global_load_lds_dwordx4 v[202:203], off
	s_waitcnt lgkmcnt(8)
	s_barrier
	s_waitcnt lgkmcnt(0)
	s_waitcnt lgkmcnt(0)
	v_mfma_f32_16x16x32_bf16 v[124:127], v[142:145], v[158:161], v[124:127]
	v_mfma_f32_16x16x32_bf16 v[120:123], v[150:153], v[158:161], v[120:123]
	v_mfma_f32_16x16x32_bf16 v[108:111], v[142:145], v[166:169], v[108:111]
	v_mfma_f32_16x16x32_bf16 v[104:107], v[150:153], v[166:169], v[104:107]
	v_mfma_f32_16x16x32_bf16 v[92:95], v[142:145], v[174:177], v[92:95]
	v_mfma_f32_16x16x32_bf16 v[88:91], v[150:153], v[174:177], v[88:91]
	v_mfma_f32_16x16x32_bf16 v[76:79], v[142:145], v[182:185], v[76:79]
	v_mfma_f32_16x16x32_bf16 v[72:75], v[150:153], v[182:185], v[72:75]
	v_mfma_f32_16x16x32_bf16 v[124:127], v[146:149], v[162:165], v[124:127]
	v_mfma_f32_16x16x32_bf16 v[120:123], v[154:157], v[162:165], v[120:123]
	v_mfma_f32_16x16x32_bf16 v[108:111], v[146:149], v[170:173], v[108:111]
	v_mfma_f32_16x16x32_bf16 v[104:107], v[154:157], v[170:173], v[104:107]
	v_mfma_f32_16x16x32_bf16 v[92:95], v[146:149], v[178:181], v[92:95]
	v_mfma_f32_16x16x32_bf16 v[88:91], v[154:157], v[178:181], v[88:91]
	v_mfma_f32_16x16x32_bf16 v[76:79], v[146:149], v[186:189], v[76:79]
	v_mfma_f32_16x16x32_bf16 v[72:75], v[154:157], v[186:189], v[72:75]
	s_barrier
	s_add_i32 s26, 0, 0x1c000
	s_add_i32 s27, s34, s39
	v_add_u32_e32 v193, s26, v140
	v_lshl_add_u64 v[190:191], v[190:191], 0, s[52:53]
	s_mov_b32 m0, s27
	ds_read_b128 v[202:205], v193
	ds_read_b128 v[206:209], v193 offset:1024
	ds_read_b128 v[210:213], v193 offset:2048
	ds_read_b128 v[214:217], v193 offset:3072
	global_load_lds_dwordx4 v[190:191], off
	v_lshl_add_u64 v[190:191], v[218:219], 0, s[52:53]
	s_add_i32 m0, s27, 0x2000
	s_nop 0
	global_load_lds_dwordx4 v[190:191], off
	s_barrier
; #define PG8_STAGE(bufoff, gbase, voff) do { _Pragma("unroll") for (int _i = 0; _i < 2; ++_i) \
;         __builtin_amdgcn_global_load_lds((const unsigned*)((const char*)(gbase) + (voff)[_i]), (LAS unsigned*)(lds + (bufoff) + ldsw + _i * 8192), 16, 0, 0); } while (0)
; #define PG8_LDA(dst, b, h) do { _Pragma("unroll") for (int m = 0; m < 4; ++m) _Pragma("unroll") for (int k = 0; k < 2; ++k) dst[m][k] = *(const LAS bf16x8*)(lds + PG8_SA(b, h) + aoff + m * 2048 + k * 1024); } while (0)
; #define PG8_LDB(dst, b, h) do { _Pragma("unroll") for (int n = 0; n < 2; ++n) _Pragma("unroll") for (int k = 0; k < 2; ++k) dst[n][k] = *(const LAS bf16x8*)(lds + PG8_SB(b, h) + boff + n * 2048 + k * 1024); } while (0)
; #define PG8_MMA(ai, bj, At, Bt) do { __builtin_amdgcn_s_setprio(1); _Pragma("unroll") for (int m = 0; m < 4; ++m) _Pragma("unroll") for (int n = 0; n < 2; ++n) _Pragma("unroll") for (int k = 0; k < 2; ++k) \
;         acc[ai][bj][m][n] = __builtin_amdgcn_mfma_f32_16x16x32_bf16(Bt[n][k], At[m][k], acc[ai][bj][m][n], 0, 0, 0); __builtin_amdgcn_s_setprio(0); } while (0)
; #define PG8_WAIT_V(n) asm volatile("s_waitcnt vmcnt(" #n ")" ::: "memory")
; #define PG8_WAIT_L(n) asm volatile("s_waitcnt lgkmcnt(" #n ")" ::: "memory")
; #define PG8_BAR __builtin_amdgcn_s_barrier()
; #define PG8_SCHED __builtin_amdgcn_sched_barrier(0)
; template <class Epi>
; __device__ __forceinline__ void gemm_phase(LAS unsigned char* lds, const Gemm g, const StaticOrder& S, const Epi& E) {
;     ...
;             PG8_LDB(B1, 1, 1); PG8_STAGE(PG8_SB(1, 0), b3, voffB);
;             PG8_BAR; PG8_WAIT_L(0); PG8_MMA(0, 1, At, B1); PG8_BAR;
;             PG8_LDA(At, 1, 1); PG8_STAGE(PG8_SA(1, 0), a3, voffA);
;             PG8_BAR; PG8_WAIT_L(0); PG8_MMA(1, 0, At, B0); PG8_BAR; PG8_SCHED;
;             PG8_STAGE(PG8_SB(1, 1), b3 + hstep, voffB);
;             PG8_WAIT_V(6); PG8_BAR; PG8_MMA(1, 1, At, B1); PG8_BAR;
;         }
	s_waitcnt lgkmcnt(0)
	s_waitcnt lgkmcnt(0)
	v_mfma_f32_16x16x32_bf16 v[116:119], v[202:205], v[158:161], v[116:119]
	v_mfma_f32_16x16x32_bf16 v[112:115], v[210:213], v[158:161], v[112:115]
	v_mfma_f32_16x16x32_bf16 v[100:103], v[202:205], v[166:169], v[100:103]
	v_mfma_f32_16x16x32_bf16 v[96:99], v[210:213], v[166:169], v[96:99]
	v_mfma_f32_16x16x32_bf16 v[84:87], v[202:205], v[174:177], v[84:87]
	v_mfma_f32_16x16x32_bf16 v[80:83], v[210:213], v[174:177], v[80:83]
	v_mfma_f32_16x16x32_bf16 v[68:71], v[202:205], v[182:185], v[68:71]
	v_mfma_f32_16x16x32_bf16 v[64:67], v[210:213], v[182:185], v[64:67]
	v_mfma_f32_16x16x32_bf16 v[116:119], v[206:209], v[162:165], v[116:119]
	v_mfma_f32_16x16x32_bf16 v[112:115], v[214:217], v[162:165], v[112:115]
	v_mfma_f32_16x16x32_bf16 v[100:103], v[206:209], v[170:173], v[100:103]
	v_mfma_f32_16x16x32_bf16 v[96:99], v[214:217], v[170:173], v[96:99]
	v_mfma_f32_16x16x32_bf16 v[84:87], v[206:209], v[178:181], v[84:87]
	v_mfma_f32_16x16x32_bf16 v[80:83], v[214:217], v[178:181], v[80:83]
	v_mfma_f32_16x16x32_bf16 v[68:71], v[206:209], v[186:189], v[68:71]
	v_mfma_f32_16x16x32_bf16 v[64:67], v[214:217], v[186:189], v[64:67]
	s_mov_b32 m0, s44
	v_lshl_add_u64 v[190:191], v[220:221], 0, s[52:53]
	s_barrier
	ds_read_b128 v[158:161], v141 offset:49152
	ds_read_b128 v[162:165], v141 offset:50176
	ds_read_b128 v[166:169], v141 offset:51200
	ds_read_b128 v[170:173], v141 offset:52224
	ds_read_b128 v[174:177], v141 offset:53248
	ds_read_b128 v[178:181], v141 offset:54272
	ds_read_b128 v[182:185], v141 offset:55296
	ds_read_b128 v[186:189], v141 offset:56320
	global_load_lds_dwordx4 v[190:191], off
	v_lshl_add_u64 v[190:191], v[222:223], 0, s[52:53]
	s_mov_b32 m0, s45
	s_nop 0
	global_load_lds_dwordx4 v[190:191], off
	s_barrier
	s_waitcnt lgkmcnt(0)
	s_waitcnt lgkmcnt(0)
	v_mfma_f32_16x16x32_bf16 v[60:63], v[142:145], v[158:161], v[60:63]
	v_mfma_f32_16x16x32_bf16 v[56:59], v[150:153], v[158:161], v[56:59]
	v_mfma_f32_16x16x32_bf16 v[44:47], v[142:145], v[166:169], v[44:47]
	v_mfma_f32_16x16x32_bf16 v[40:43], v[150:153], v[166:169], v[40:43]
	v_mfma_f32_16x16x32_bf16 v[28:31], v[142:145], v[174:177], v[28:31]
	v_mfma_f32_16x16x32_bf16 v[24:27], v[150:153], v[174:177], v[24:27]
	v_mfma_f32_16x16x32_bf16 v[12:15], v[142:145], v[182:185], v[12:15]
	v_mfma_f32_16x16x32_bf16 v[8:11], v[150:153], v[182:185], v[8:11]
	v_mfma_f32_16x16x32_bf16 v[60:63], v[146:149], v[162:165], v[60:63]
	v_mfma_f32_16x16x32_bf16 v[56:59], v[154:157], v[162:165], v[56:59]
	v_mfma_f32_16x16x32_bf16 v[44:47], v[146:149], v[170:173], v[44:47]
	v_mfma_f32_16x16x32_bf16 v[40:43], v[154:157], v[170:173], v[40:43]
	v_mfma_f32_16x16x32_bf16 v[28:31], v[146:149], v[178:181], v[28:31]
	v_mfma_f32_16x16x32_bf16 v[24:27], v[154:157], v[178:181], v[24:27]
	v_mfma_f32_16x16x32_bf16 v[12:15], v[146:149], v[186:189], v[12:15]
	v_mfma_f32_16x16x32_bf16 v[8:11], v[154:157], v[186:189], v[8:11]
	s_barrier
	s_add_i32 s26, s26, s39
	v_lshl_add_u64 v[142:143], v[224:225], 0, s[52:53]
	s_mov_b32 m0, s26
	s_nop 0
	global_load_lds_dwordx4 v[142:143], off
	v_lshl_add_u64 v[142:143], v[226:227], 0, s[52:53]
	s_add_i32 m0, s26, 0x2000
	s_nop 0
	global_load_lds_dwordx4 v[142:143], off
	s_waitcnt vmcnt(6)
	s_barrier
	v_mfma_f32_16x16x32_bf16 v[52:55], v[202:205], v[158:161], v[52:55]
	v_mfma_f32_16x16x32_bf16 v[48:51], v[210:213], v[158:161], v[48:51]
	v_mfma_f32_16x16x32_bf16 v[36:39], v[202:205], v[166:169], v[36:39]
	v_mfma_f32_16x16x32_bf16 v[32:35], v[210:213], v[166:169], v[32:35]
	v_mfma_f32_16x16x32_bf16 v[20:23], v[202:205], v[174:177], v[20:23]
	v_mfma_f32_16x16x32_bf16 v[16:19], v[210:213], v[174:177], v[16:19]
	v_mfma_f32_16x16x32_bf16 v[4:7], v[202:205], v[182:185], v[4:7]
	v_mfma_f32_16x16x32_bf16 v[0:3], v[210:213], v[182:185], v[0:3]
	v_mfma_f32_16x16x32_bf16 v[52:55], v[206:209], v[162:165], v[52:55]
	v_mfma_f32_16x16x32_bf16 v[48:51], v[214:217], v[162:165], v[48:51]
	v_mfma_f32_16x16x32_bf16 v[36:39], v[206:209], v[170:173], v[36:39]
	v_mfma_f32_16x16x32_bf16 v[32:35], v[214:217], v[170:173], v[32:35]
	v_mfma_f32_16x16x32_bf16 v[20:23], v[206:209], v[178:181], v[20:23]
	v_mfma_f32_16x16x32_bf16 v[16:19], v[214:217], v[178:181], v[16:19]
	v_mfma_f32_16x16x32_bf16 v[4:7], v[206:209], v[186:189], v[4:7]
	v_mfma_f32_16x16x32_bf16 v[0:3], v[214:217], v[186:189], v[0:3]
	s_cmp_ge_i32 s48, s46
	s_mov_b64 s[26:27], s[28:29]
	s_mov_b32 s30, s48
	s_barrier
	s_cbranch_scc0 .LBB0_433

; #define PG8_STAGE(bufoff, gbase, voff) do { _Pragma("unroll") for (int _i = 0; _i < 2; ++_i) \
;         __builtin_amdgcn_global_load_lds((const unsigned*)((const char*)(gbase) + (voff)[_i]), (LAS unsigned*)(lds + (bufoff) + ldsw + _i * 8192), 16, 0, 0); } while (0)
; #define PG8_LDA(dst, b, h) do { _Pragma("unroll") for (int m = 0; m < 4; ++m) _Pragma("unroll") for (int k = 0; k < 2; ++k) dst[m][k] = *(const LAS bf16x8*)(lds + PG8_SA(b, h) + aoff + m * 2048 + k * 1024); } while (0)
; #define PG8_LDB(dst, b, h) do { _Pragma("unroll") for (int n = 0; n < 2; ++n) _Pragma("unroll") for (int k = 0; k < 2; ++k) dst[n][k] = *(const LAS bf16x8*)(lds + PG8_SB(b, h) + boff + n * 2048 + k * 1024); } while (0)
; #define PG8_MMA(ai, bj, At, Bt) do { __builtin_amdgcn_s_setprio(1); _Pragma("unroll") for (int m = 0; m < 4; ++m) _Pragma("unroll") for (int n = 0; n < 2; ++n) _Pragma("unroll") for (int k = 0; k < 2; ++k) \
;         acc[ai][bj][m][n] = __builtin_amdgcn_mfma_f32_16x16x32_bf16(Bt[n][k], At[m][k], acc[ai][bj][m][n], 0, 0, 0); __builtin_amdgcn_s_setprio(0); } while (0)
; #define PG8_WAIT_L(n) asm volatile("s_waitcnt lgkmcnt(" #n ")" ::: "memory")
; #define PG8_BAR __builtin_amdgcn_s_barrier()
; #define PG8_SCHED __builtin_amdgcn_sched_barrier(0)
; template <class Epi>
; __device__ __forceinline__ void gemm_phase(LAS unsigned char* lds, const Gemm g, const StaticOrder& S, const Epi& E) {
;     ...
;             PG8_LDB(B0, 0, 0); PG8_SCHED; PG8_LDA(At, 0, 0); PG8_STAGE(PG8_SA(1, 1), a1 + hstep, voffA);
;             PG8_WAIT_L(8); PG8_BAR; PG8_WAIT_L(0); PG8_MMA(0, 0, At, B0); PG8_BAR; PG8_SCHED;
;             PG8_LDB(B1, 0, 1); PG8_STAGE(PG8_SB(0, 0), b2, voffB);
;             PG8_BAR; PG8_WAIT_L(0); PG8_MMA(0, 1, At, B1); PG8_BAR;
;             PG8_LDA(At, 0, 1); PG8_STAGE(PG8_SA(0, 0), a2, voffA);
;             PG8_BAR; PG8_WAIT_L(0); PG8_MMA(1, 0, At, B0); PG8_BAR; PG8_SCHED;
.LBB0_460:
	s_add_i32 s59, s36, 2
	s_add_u32 s38, s34, 0x80
	s_addc_u32 s37, s35, 0
	s_add_i32 s60, 0, 0x10000
	v_add_u32_e32 v140, s60, v143
	ds_read_b128 v[146:149], v140
	ds_read_b128 v[150:153], v140 offset:1024
	ds_read_b128 v[154:157], v140 offset:2048
	ds_read_b128 v[158:161], v140 offset:3072
	s_cmp_eq_u32 s51, s36
	s_cselect_b32 s36, s28, s38
	s_cselect_b32 s37, s29, s37
	s_cselect_b32 s39, s31, s58
	s_cselect_b32 s38, s30, s57
	v_lshl_add_u64 v[140:141], s[34:35], 0, v[138:139]
	s_add_i32 m0, s44, 0xc000
	ds_read_b128 v[162:165], v144
	ds_read_b128 v[166:169], v144 offset:1024
	ds_read_b128 v[170:173], v144 offset:2048
	ds_read_b128 v[174:177], v144 offset:3072
	ds_read_b128 v[178:181], v144 offset:4096
	ds_read_b128 v[182:185], v144 offset:5120
	ds_read_b128 v[186:189], v144 offset:6144
	ds_read_b128 v[202:205], v144 offset:7168
	global_load_lds_dwordx4 v[140:141], off
	v_lshl_add_u64 v[140:141], s[34:35], 0, v[136:137]
	s_add_i32 m0, s44, 0xe000
	s_nop 0
	global_load_lds_dwordx4 v[140:141], off
	s_waitcnt lgkmcnt(8)
	s_barrier
	s_waitcnt lgkmcnt(0)
	s_waitcnt lgkmcnt(0)
	v_mfma_f32_16x16x32_bf16 v[124:127], v[146:149], v[162:165], v[124:127]
	v_mfma_f32_16x16x32_bf16 v[120:123], v[154:157], v[162:165], v[120:123]
	v_mfma_f32_16x16x32_bf16 v[108:111], v[146:149], v[170:173], v[108:111]
	v_mfma_f32_16x16x32_bf16 v[104:107], v[154:157], v[170:173], v[104:107]
	v_mfma_f32_16x16x32_bf16 v[92:95], v[146:149], v[178:181], v[92:95]
	v_mfma_f32_16x16x32_bf16 v[88:91], v[154:157], v[178:181], v[88:91]
	v_mfma_f32_16x16x32_bf16 v[76:79], v[146:149], v[186:189], v[76:79]
	v_mfma_f32_16x16x32_bf16 v[72:75], v[154:157], v[186:189], v[72:75]
	v_mfma_f32_16x16x32_bf16 v[124:127], v[150:153], v[166:169], v[124:127]
	v_mfma_f32_16x16x32_bf16 v[120:123], v[158:161], v[166:169], v[120:123]
	v_mfma_f32_16x16x32_bf16 v[108:111], v[150:153], v[174:177], v[108:111]
	v_mfma_f32_16x16x32_bf16 v[104:107], v[158:161], v[174:177], v[104:107]
	v_mfma_f32_16x16x32_bf16 v[92:95], v[150:153], v[182:185], v[92:95]
	v_mfma_f32_16x16x32_bf16 v[88:91], v[158:161], v[182:185], v[88:91]
	v_mfma_f32_16x16x32_bf16 v[76:79], v[150:153], v[202:205], v[76:79]
	v_mfma_f32_16x16x32_bf16 v[72:75], v[158:161], v[202:205], v[72:75]
	s_barrier
	s_add_i32 s61, 0, 0x14000
	v_add_u32_e32 v140, s61, v143
	s_add_i32 s60, s60, s43
	ds_read_b128 v[206:209], v140
	ds_read_b128 v[210:213], v140 offset:1024
	ds_read_b128 v[214:217], v140 offset:2048
	ds_read_b128 v[218:221], v140 offset:3072
	v_lshl_add_u64 v[140:141], s[38:39], 0, v[194:195]
	s_mov_b32 m0, s60
	v_lshl_add_u64 v[190:191], s[38:39], 0, v[132:133]
	global_load_lds_dwordx4 v[140:141], off
	s_add_i32 m0, s60, 0x2000
	s_nop 0
	global_load_lds_dwordx4 v[190:191], off
	s_barrier
	s_waitcnt lgkmcnt(0)
	s_waitcnt lgkmcnt(0)
	v_mfma_f32_16x16x32_bf16 v[116:119], v[206:209], v[162:165], v[116:119]
	v_mfma_f32_16x16x32_bf16 v[112:115], v[214:217], v[162:165], v[112:115]
	v_mfma_f32_16x16x32_bf16 v[100:103], v[206:209], v[170:173], v[100:103]
	v_mfma_f32_16x16x32_bf16 v[96:99], v[214:217], v[170:173], v[96:99]
	v_mfma_f32_16x16x32_bf16 v[84:87], v[206:209], v[178:181], v[84:87]
	v_mfma_f32_16x16x32_bf16 v[80:83], v[214:217], v[178:181], v[80:83]
	v_mfma_f32_16x16x32_bf16 v[68:71], v[206:209], v[186:189], v[68:71]
	v_mfma_f32_16x16x32_bf16 v[64:67], v[214:217], v[186:189], v[64:67]
	v_mfma_f32_16x16x32_bf16 v[116:119], v[210:213], v[166:169], v[116:119]
	v_mfma_f32_16x16x32_bf16 v[112:115], v[218:221], v[166:169], v[112:115]
	v_mfma_f32_16x16x32_bf16 v[100:103], v[210:213], v[174:177], v[100:103]
	v_mfma_f32_16x16x32_bf16 v[96:99], v[218:221], v[174:177], v[96:99]
	v_mfma_f32_16x16x32_bf16 v[84:87], v[210:213], v[182:185], v[84:87]
	v_mfma_f32_16x16x32_bf16 v[80:83], v[218:221], v[182:185], v[80:83]
	v_mfma_f32_16x16x32_bf16 v[68:71], v[210:213], v[202:205], v[68:71]
	v_mfma_f32_16x16x32_bf16 v[64:67], v[218:221], v[202:205], v[64:67]
	s_mov_b32 m0, s44
	v_lshl_add_u64 v[222:223], s[36:37], 0, v[128:129]
	s_barrier
	ds_read_b128 v[162:165], v144 offset:16384
	ds_read_b128 v[166:169], v144 offset:17408
	ds_read_b128 v[170:173], v144 offset:18432
	ds_read_b128 v[174:177], v144 offset:19456
	ds_read_b128 v[178:181], v144 offset:20480
	ds_read_b128 v[182:185], v144 offset:21504
	ds_read_b128 v[186:189], v144 offset:22528
	ds_read_b128 v[202:205], v144 offset:23552
	global_load_lds_dwordx4 v[222:223], off
	v_lshl_add_u64 v[224:225], s[36:37], 0, v[130:131]
	s_mov_b32 m0, s45
	s_nop 0
	global_load_lds_dwordx4 v[224:225], off
	s_barrier
	s_waitcnt lgkmcnt(0)
	s_waitcnt lgkmcnt(0)
	v_mfma_f32_16x16x32_bf16 v[60:63], v[146:149], v[162:165], v[60:63]
	v_mfma_f32_16x16x32_bf16 v[56:59], v[154:157], v[162:165], v[56:59]
	v_mfma_f32_16x16x32_bf16 v[44:47], v[146:149], v[170:173], v[44:47]
	v_mfma_f32_16x16x32_bf16 v[40:43], v[154:157], v[170:173], v[40:43]
	v_mfma_f32_16x16x32_bf16 v[28:31], v[146:149], v[178:181], v[28:31]
	v_mfma_f32_16x16x32_bf16 v[24:27], v[154:157], v[178:181], v[24:27]
	v_mfma_f32_16x16x32_bf16 v[12:15], v[146:149], v[186:189], v[12:15]
	v_mfma_f32_16x16x32_bf16 v[8:11], v[154:157], v[186:189], v[8:11]
	v_mfma_f32_16x16x32_bf16 v[60:63], v[150:153], v[166:169], v[60:63]
	v_mfma_f32_16x16x32_bf16 v[56:59], v[158:161], v[166:169], v[56:59]
	v_mfma_f32_16x16x32_bf16 v[44:47], v[150:153], v[174:177], v[44:47]
	v_mfma_f32_16x16x32_bf16 v[40:43], v[158:161], v[174:177], v[40:43]
	v_mfma_f32_16x16x32_bf16 v[28:31], v[150:153], v[182:185], v[28:31]
	v_mfma_f32_16x16x32_bf16 v[24:27], v[158:161], v[182:185], v[24:27]
	v_mfma_f32_16x16x32_bf16 v[12:15], v[150:153], v[202:205], v[12:15]
	v_mfma_f32_16x16x32_bf16 v[8:11], v[158:161], v[202:205], v[8:11]
	s_barrier
; #define PG8_STAGE(bufoff, gbase, voff) do { _Pragma("unroll") for (int _i = 0; _i < 2; ++_i) \
;         __builtin_amdgcn_global_load_lds((const unsigned*)((const char*)(gbase) + (voff)[_i]), (LAS unsigned*)(lds + (bufoff) + ldsw + _i * 8192), 16, 0, 0); } while (0)
; #define PG8_LDA(dst, b, h) do { _Pragma("unroll") for (int m = 0; m < 4; ++m) _Pragma("unroll") for (int k = 0; k < 2; ++k) dst[m][k] = *(const LAS bf16x8*)(lds + PG8_SA(b, h) + aoff + m * 2048 + k * 1024); } while (0)
; #define PG8_LDB(dst, b, h) do { _Pragma("unroll") for (int n = 0; n < 2; ++n) _Pragma("unroll") for (int k = 0; k < 2; ++k) dst[n][k] = *(const LAS bf16x8*)(lds + PG8_SB(b, h) + boff + n * 2048 + k * 1024); } while (0)
; #define PG8_MMA(ai, bj, At, Bt) do { __builtin_amdgcn_s_setprio(1); _Pragma("unroll") for (int m = 0; m < 4; ++m) _Pragma("unroll") for (int n = 0; n < 2; ++n) _Pragma("unroll") for (int k = 0; k < 2; ++k) \
;         acc[ai][bj][m][n] = __builtin_amdgcn_mfma_f32_16x16x32_bf16(Bt[n][k], At[m][k], acc[ai][bj][m][n], 0, 0, 0); __builtin_amdgcn_s_setprio(0); } while (0)
; #define PG8_WAIT_V(n) asm volatile("s_waitcnt vmcnt(" #n ")" ::: "memory")
; #define PG8_WAIT_L(n) asm volatile("s_waitcnt lgkmcnt(" #n ")" ::: "memory")
; #define PG8_BAR __builtin_amdgcn_s_barrier()
; #define PG8_SCHED __builtin_amdgcn_sched_barrier(0)
; template <class Epi>
; __device__ __forceinline__ void gemm_phase(LAS unsigned char* lds, const Gemm g, const StaticOrder& S, const Epi& E) {
;     ...
;             PG8_STAGE(PG8_SB(0, 1), b2 + hstep, voffB);
;             PG8_WAIT_V(6); PG8_BAR; PG8_MMA(1, 1, At, B1); PG8_BAR;
;             PG8_LDB(B0, 1, 0); PG8_SCHED; PG8_LDA(At, 1, 0); PG8_STAGE(PG8_SA(0, 1), a2 + hstep, voffA);
;             PG8_WAIT_L(8); PG8_BAR; PG8_WAIT_L(0); PG8_MMA(0, 0, At, B0); PG8_BAR; PG8_SCHED;
;             PG8_LDB(B1, 1, 1); PG8_STAGE(PG8_SB(1, 0), b3, voffB);
	s_add_u32 s38, s38, s4
	s_addc_u32 s39, s39, s5
	s_add_i32 s60, s61, s43
	v_lshl_add_u64 v[226:227], s[38:39], 0, v[194:195]
	s_mov_b32 m0, s60
	v_lshl_add_u64 v[228:229], s[38:39], 0, v[132:133]
	global_load_lds_dwordx4 v[226:227], off
	s_add_i32 m0, s60, 0x2000
	s_nop 0
	global_load_lds_dwordx4 v[228:229], off
	s_waitcnt vmcnt(6)
	s_barrier
	v_mfma_f32_16x16x32_bf16 v[52:55], v[206:209], v[162:165], v[52:55]
	v_mfma_f32_16x16x32_bf16 v[48:51], v[214:217], v[162:165], v[48:51]
	v_mfma_f32_16x16x32_bf16 v[36:39], v[206:209], v[170:173], v[36:39]
	v_mfma_f32_16x16x32_bf16 v[32:35], v[214:217], v[170:173], v[32:35]
	v_mfma_f32_16x16x32_bf16 v[20:23], v[206:209], v[178:181], v[20:23]
	v_mfma_f32_16x16x32_bf16 v[16:19], v[214:217], v[178:181], v[16:19]
	v_mfma_f32_16x16x32_bf16 v[4:7], v[206:209], v[186:189], v[4:7]
	v_mfma_f32_16x16x32_bf16 v[0:3], v[214:217], v[186:189], v[0:3]
	v_mfma_f32_16x16x32_bf16 v[52:55], v[210:213], v[166:169], v[52:55]
	v_mfma_f32_16x16x32_bf16 v[48:51], v[218:221], v[166:169], v[48:51]
	v_mfma_f32_16x16x32_bf16 v[36:39], v[210:213], v[174:177], v[36:39]
	v_mfma_f32_16x16x32_bf16 v[32:35], v[218:221], v[174:177], v[32:35]
	v_mfma_f32_16x16x32_bf16 v[20:23], v[210:213], v[182:185], v[20:23]
	v_mfma_f32_16x16x32_bf16 v[16:19], v[218:221], v[182:185], v[16:19]
	v_mfma_f32_16x16x32_bf16 v[4:7], v[210:213], v[202:205], v[4:7]
	v_mfma_f32_16x16x32_bf16 v[0:3], v[218:221], v[202:205], v[0:3]
	s_add_i32 s38, 0, 0x18000
	v_add_u32_e32 v145, s38, v143
	s_barrier
	ds_read_b128 v[146:149], v145
	ds_read_b128 v[150:153], v145 offset:1024
	ds_read_b128 v[154:157], v145 offset:2048
	ds_read_b128 v[158:161], v145 offset:3072
	s_add_u32 s36, s36, s4
	s_addc_u32 s37, s37, s5
	s_mov_b32 m0, s46
	v_lshl_add_u64 v[206:207], s[36:37], 0, v[128:129]
	ds_read_b128 v[162:165], v144 offset:32768
	ds_read_b128 v[166:169], v144 offset:33792
	ds_read_b128 v[170:173], v144 offset:34816
	ds_read_b128 v[174:177], v144 offset:35840
	ds_read_b128 v[178:181], v144 offset:36864
	ds_read_b128 v[182:185], v144 offset:37888
	ds_read_b128 v[186:189], v144 offset:38912
	ds_read_b128 v[202:205], v144 offset:39936
	global_load_lds_dwordx4 v[206:207], off
	v_lshl_add_u64 v[206:207], s[36:37], 0, v[130:131]
	s_mov_b32 m0, s47
	s_nop 0
	global_load_lds_dwordx4 v[206:207], off
	s_waitcnt lgkmcnt(8)
	s_barrier
	s_waitcnt lgkmcnt(0)
	s_waitcnt lgkmcnt(0)
	v_mfma_f32_16x16x32_bf16 v[124:127], v[146:149], v[162:165], v[124:127]
	v_mfma_f32_16x16x32_bf16 v[120:123], v[154:157], v[162:165], v[120:123]
	v_mfma_f32_16x16x32_bf16 v[108:111], v[146:149], v[170:173], v[108:111]
	v_mfma_f32_16x16x32_bf16 v[104:107], v[154:157], v[170:173], v[104:107]
	v_mfma_f32_16x16x32_bf16 v[92:95], v[146:149], v[178:181], v[92:95]
	v_mfma_f32_16x16x32_bf16 v[88:91], v[154:157], v[178:181], v[88:91]
	v_mfma_f32_16x16x32_bf16 v[76:79], v[146:149], v[186:189], v[76:79]
	v_mfma_f32_16x16x32_bf16 v[72:75], v[154:157], v[186:189], v[72:75]
	v_mfma_f32_16x16x32_bf16 v[124:127], v[150:153], v[166:169], v[124:127]
	v_mfma_f32_16x16x32_bf16 v[120:123], v[158:161], v[166:169], v[120:123]
	v_mfma_f32_16x16x32_bf16 v[108:111], v[150:153], v[174:177], v[108:111]
	v_mfma_f32_16x16x32_bf16 v[104:107], v[158:161], v[174:177], v[104:107]
	v_mfma_f32_16x16x32_bf16 v[92:95], v[150:153], v[182:185], v[92:95]
	v_mfma_f32_16x16x32_bf16 v[88:91], v[158:161], v[182:185], v[88:91]
	v_mfma_f32_16x16x32_bf16 v[76:79], v[150:153], v[202:205], v[76:79]
	v_mfma_f32_16x16x32_bf16 v[72:75], v[158:161], v[202:205], v[72:75]
	s_barrier
	s_add_i32 s36, 0, 0x1c000
	s_add_i32 s37, s38, s43
	v_add_u32_e32 v145, s36, v143
	v_lshl_add_u64 v[140:141], v[140:141], 0, s[64:65]
	s_mov_b32 m0, s37
	ds_read_b128 v[206:209], v145
	ds_read_b128 v[210:213], v145 offset:1024
	ds_read_b128 v[214:217], v145 offset:2048
	ds_read_b128 v[218:221], v145 offset:3072
	global_load_lds_dwordx4 v[140:141], off
	v_lshl_add_u64 v[140:141], v[190:191], 0, s[64:65]
	s_add_i32 m0, s37, 0x2000
	s_nop 0
	global_load_lds_dwordx4 v[140:141], off
	s_barrier
; #define PG8_STAGE(bufoff, gbase, voff) do { _Pragma("unroll") for (int _i = 0; _i < 2; ++_i) \
;         __builtin_amdgcn_global_load_lds((const unsigned*)((const char*)(gbase) + (voff)[_i]), (LAS unsigned*)(lds + (bufoff) + ldsw + _i * 8192), 16, 0, 0); } while (0)
; #define PG8_LDA(dst, b, h) do { _Pragma("unroll") for (int m = 0; m < 4; ++m) _Pragma("unroll") for (int k = 0; k < 2; ++k) dst[m][k] = *(const LAS bf16x8*)(lds + PG8_SA(b, h) + aoff + m * 2048 + k * 1024); } while (0)
; #define PG8_LDB(dst, b, h) do { _Pragma("unroll") for (int n = 0; n < 2; ++n) _Pragma("unroll") for (int k = 0; k < 2; ++k) dst[n][k] = *(const LAS bf16x8*)(lds + PG8_SB(b, h) + boff + n * 2048 + k * 1024); } while (0)
; #define PG8_MMA(ai, bj, At, Bt) do { __builtin_amdgcn_s_setprio(1); _Pragma("unroll") for (int m = 0; m < 4; ++m) _Pragma("unroll") for (int n = 0; n < 2; ++n) _Pragma("unroll") for (int k = 0; k < 2; ++k) \
;         acc[ai][bj][m][n] = __builtin_amdgcn_mfma_f32_16x16x32_bf16(Bt[n][k], At[m][k], acc[ai][bj][m][n], 0, 0, 0); __builtin_amdgcn_s_setprio(0); } while (0)
; #define PG8_WAIT_V(n) asm volatile("s_waitcnt vmcnt(" #n ")" ::: "memory")
; #define PG8_WAIT_L(n) asm volatile("s_waitcnt lgkmcnt(" #n ")" ::: "memory")
; #define PG8_BAR __builtin_amdgcn_s_barrier()
; #define PG8_SCHED __builtin_amdgcn_sched_barrier(0)
; template <class Epi>
; __device__ __forceinline__ void gemm_phase(LAS unsigned char* lds, const Gemm g, const StaticOrder& S, const Epi& E) {
;     ...
;             PG8_LDB(B1, 1, 1); PG8_STAGE(PG8_SB(1, 0), b3, voffB);
;             PG8_BAR; PG8_WAIT_L(0); PG8_MMA(0, 1, At, B1); PG8_BAR;
;             PG8_LDA(At, 1, 1); PG8_STAGE(PG8_SA(1, 0), a3, voffA);
;             PG8_BAR; PG8_WAIT_L(0); PG8_MMA(1, 0, At, B0); PG8_BAR; PG8_SCHED;
;             PG8_STAGE(PG8_SB(1, 1), b3 + hstep, voffB);
;             PG8_WAIT_V(6); PG8_BAR; PG8_MMA(1, 1, At, B1); PG8_BAR;
;         }
	s_waitcnt lgkmcnt(0)
	s_waitcnt lgkmcnt(0)
	v_mfma_f32_16x16x32_bf16 v[116:119], v[206:209], v[162:165], v[116:119]
	v_mfma_f32_16x16x32_bf16 v[112:115], v[214:217], v[162:165], v[112:115]
	v_mfma_f32_16x16x32_bf16 v[100:103], v[206:209], v[170:173], v[100:103]
	v_mfma_f32_16x16x32_bf16 v[96:99], v[214:217], v[170:173], v[96:99]
	v_mfma_f32_16x16x32_bf16 v[84:87], v[206:209], v[178:181], v[84:87]
	v_mfma_f32_16x16x32_bf16 v[80:83], v[214:217], v[178:181], v[80:83]
	v_mfma_f32_16x16x32_bf16 v[68:71], v[206:209], v[186:189], v[68:71]
	v_mfma_f32_16x16x32_bf16 v[64:67], v[214:217], v[186:189], v[64:67]
	v_mfma_f32_16x16x32_bf16 v[116:119], v[210:213], v[166:169], v[116:119]
	v_mfma_f32_16x16x32_bf16 v[112:115], v[218:221], v[166:169], v[112:115]
	v_mfma_f32_16x16x32_bf16 v[100:103], v[210:213], v[174:177], v[100:103]
	v_mfma_f32_16x16x32_bf16 v[96:99], v[218:221], v[174:177], v[96:99]
	v_mfma_f32_16x16x32_bf16 v[84:87], v[210:213], v[182:185], v[84:87]
	v_mfma_f32_16x16x32_bf16 v[80:83], v[218:221], v[182:185], v[80:83]
	v_mfma_f32_16x16x32_bf16 v[68:71], v[210:213], v[202:205], v[68:71]
	v_mfma_f32_16x16x32_bf16 v[64:67], v[218:221], v[202:205], v[64:67]
	s_mov_b32 m0, s48
	v_lshl_add_u64 v[140:141], v[222:223], 0, s[64:65]
	s_barrier
	ds_read_b128 v[162:165], v144 offset:49152
	ds_read_b128 v[166:169], v144 offset:50176
	ds_read_b128 v[170:173], v144 offset:51200
	ds_read_b128 v[174:177], v144 offset:52224
	ds_read_b128 v[178:181], v144 offset:53248
	ds_read_b128 v[182:185], v144 offset:54272
	ds_read_b128 v[186:189], v144 offset:55296
	ds_read_b128 v[202:205], v144 offset:56320
	global_load_lds_dwordx4 v[140:141], off
	v_lshl_add_u64 v[140:141], v[224:225], 0, s[64:65]
	s_mov_b32 m0, s49
	s_nop 0
	global_load_lds_dwordx4 v[140:141], off
	s_barrier
	s_waitcnt lgkmcnt(0)
	s_waitcnt lgkmcnt(0)
	v_mfma_f32_16x16x32_bf16 v[60:63], v[146:149], v[162:165], v[60:63]
	v_mfma_f32_16x16x32_bf16 v[56:59], v[154:157], v[162:165], v[56:59]
	v_mfma_f32_16x16x32_bf16 v[44:47], v[146:149], v[170:173], v[44:47]
	v_mfma_f32_16x16x32_bf16 v[40:43], v[154:157], v[170:173], v[40:43]
	v_mfma_f32_16x16x32_bf16 v[28:31], v[146:149], v[178:181], v[28:31]
	v_mfma_f32_16x16x32_bf16 v[24:27], v[154:157], v[178:181], v[24:27]
	v_mfma_f32_16x16x32_bf16 v[12:15], v[146:149], v[186:189], v[12:15]
	v_mfma_f32_16x16x32_bf16 v[8:11], v[154:157], v[186:189], v[8:11]
	v_mfma_f32_16x16x32_bf16 v[60:63], v[150:153], v[166:169], v[60:63]
	v_mfma_f32_16x16x32_bf16 v[56:59], v[158:161], v[166:169], v[56:59]
	v_mfma_f32_16x16x32_bf16 v[44:47], v[150:153], v[174:177], v[44:47]
	v_mfma_f32_16x16x32_bf16 v[40:43], v[158:161], v[174:177], v[40:43]
	v_mfma_f32_16x16x32_bf16 v[28:31], v[150:153], v[182:185], v[28:31]
	v_mfma_f32_16x16x32_bf16 v[24:27], v[158:161], v[182:185], v[24:27]
	v_mfma_f32_16x16x32_bf16 v[12:15], v[150:153], v[202:205], v[12:15]
	v_mfma_f32_16x16x32_bf16 v[8:11], v[158:161], v[202:205], v[8:11]
	s_barrier
	s_add_i32 s36, s36, s43
	v_lshl_add_u64 v[140:141], v[226:227], 0, s[64:65]
	s_mov_b32 m0, s36
	s_nop 0
	global_load_lds_dwordx4 v[140:141], off
	v_lshl_add_u64 v[140:141], v[228:229], 0, s[64:65]
	s_add_i32 m0, s36, 0x2000
	s_nop 0
	global_load_lds_dwordx4 v[140:141], off
	s_waitcnt vmcnt(6)
	s_barrier
	v_mfma_f32_16x16x32_bf16 v[52:55], v[206:209], v[162:165], v[52:55]
	v_mfma_f32_16x16x32_bf16 v[48:51], v[214:217], v[162:165], v[48:51]
	v_mfma_f32_16x16x32_bf16 v[36:39], v[206:209], v[170:173], v[36:39]
	v_mfma_f32_16x16x32_bf16 v[32:35], v[214:217], v[170:173], v[32:35]
	v_mfma_f32_16x16x32_bf16 v[20:23], v[206:209], v[178:181], v[20:23]
	v_mfma_f32_16x16x32_bf16 v[16:19], v[214:217], v[178:181], v[16:19]
	v_mfma_f32_16x16x32_bf16 v[4:7], v[206:209], v[186:189], v[4:7]
	v_mfma_f32_16x16x32_bf16 v[0:3], v[214:217], v[186:189], v[0:3]
	v_mfma_f32_16x16x32_bf16 v[52:55], v[210:213], v[166:169], v[52:55]
	v_mfma_f32_16x16x32_bf16 v[48:51], v[218:221], v[166:169], v[48:51]
	v_mfma_f32_16x16x32_bf16 v[36:39], v[210:213], v[174:177], v[36:39]
	v_mfma_f32_16x16x32_bf16 v[32:35], v[218:221], v[174:177], v[32:35]
	v_mfma_f32_16x16x32_bf16 v[20:23], v[210:213], v[182:185], v[20:23]
	v_mfma_f32_16x16x32_bf16 v[16:19], v[218:221], v[182:185], v[16:19]
	v_mfma_f32_16x16x32_bf16 v[4:7], v[210:213], v[202:205], v[4:7]
	v_mfma_f32_16x16x32_bf16 v[0:3], v[218:221], v[202:205], v[0:3]
	s_add_u32 s57, s57, 0x100
	s_addc_u32 s58, s58, 0
	s_add_u32 s34, s34, 0x100
	s_addc_u32 s35, s35, 0
	s_cmp_ge_i32 s59, s50
	s_mov_b32 s36, s59
	s_barrier
	s_cbranch_scc0 .LBB0_460
	s_branch .LBB0_446
